# write-through (sc1) stores for P1/P2/P6/P9 outputs consumed on other XCDs (lighter L2 write-back at the following seams)
# baseline (speedup 1.0000x reference)
.LBB0_171:
	s_lshl_b64 s[42:43], s[40:41], 12
	v_pk_add_f32 v[0:1], v[0:1], v[12:13] op_sel_hi:[1,0]
	v_pk_add_f32 v[10:11], v[10:11], v[12:13] op_sel_hi:[1,0]
	s_add_i32 s40, s40, s28
	v_pk_mul_f32 v[22:23], v[10:11], s[38:39] op_sel_hi:[1,0]
	v_pk_mul_f32 v[20:21], v[0:1], s[38:39] op_sel_hi:[1,0]
	v_pk_add_f32 v[0:1], v[8:9], v[12:13] op_sel_hi:[1,0]
	v_pk_add_f32 v[2:3], v[2:3], v[12:13] op_sel_hi:[1,0]
	v_lshl_add_u64 v[8:9], s[42:43], 2, v[6:7]
	s_cmp_gt_i32 s40, 63
	v_pk_mul_f32 v[2:3], v[2:3], s[38:39] op_sel_hi:[1,0]
	v_pk_mul_f32 v[0:1], v[0:1], s[38:39] op_sel_hi:[1,0]
	global_store_dwordx4 v[8:9], v[20:23], off sc1
	global_store_dwordx4 v[8:9], v[0:3], off offset:16 sc1
	s_barrier
	s_cbranch_scc1 .LBB0_182

.LBB0_204:
	s_ashr_i32 s53, s52, 31
	s_lshl_b64 s[50:51], s[52:53], 25
	s_add_u32 s50, s70, s50
	s_addc_u32 s51, s71, s51
	v_ashrrev_i32_e32 v163, 31, v162
	v_ashrrev_i32_e32 v161, 31, v160
	v_lshl_add_u64 v[162:163], v[162:163], 1, s[50:51]
	v_lshlrev_b64 v[164:165], 11, v[160:161]
	v_pk_mul_f32 v[142:143], v[142:143], v[166:167] op_sel_hi:[1,0]
	v_pk_mul_f32 v[140:141], v[140:141], v[166:167] op_sel_hi:[1,0]
	v_pk_mul_f32 v[138:139], v[138:139], v[166:167] op_sel_hi:[1,0]
	v_pk_mul_f32 v[136:137], v[136:137], v[166:167] op_sel_hi:[1,0]
	v_lshl_add_u64 v[164:165], v[162:163], 0, v[164:165]
	s_waitcnt lgkmcnt(0)
	v_pk_mul_f32 v[142:143], v[126:127], v[142:143]
	v_pk_mul_f32 v[140:141], v[124:125], v[140:141]
	v_pk_mul_f32 v[176:177], v[122:123], v[138:139]
	v_pk_mul_f32 v[138:139], v[120:121], v[136:137]
	v_cvt_pk_bf16_f32 v136, v140, v141
	v_cvt_pk_bf16_f32 v137, v142, v143
	v_pk_mul_f32 v[130:131], v[130:131], v[166:167] op_sel_hi:[1,0]
	v_pk_mul_f32 v[128:129], v[128:129], v[166:167] op_sel_hi:[1,0]
	v_cvt_pk_bf16_f32 v138, v138, v139
	v_cvt_pk_bf16_f32 v139, v176, v177
	global_store_dwordx4 v[164:165], v[136:139], off sc1
	v_pk_mul_f32 v[134:135], v[134:135], v[166:167] op_sel_hi:[1,0]
	v_pk_mul_f32 v[132:133], v[132:133], v[166:167] op_sel_hi:[1,0]
	v_pk_mul_f32 v[136:137], v[106:107], v[130:131]
	v_pk_mul_f32 v[130:131], v[104:105], v[128:129]
	v_pk_mul_f32 v[134:135], v[110:111], v[134:135]
	v_pk_mul_f32 v[132:133], v[108:109], v[132:133]
	s_and_b64 vcc, exec, s[8:9]
	v_cvt_pk_bf16_f32 v128, v132, v133
	v_cvt_pk_bf16_f32 v129, v134, v135
	v_cvt_pk_bf16_f32 v130, v130, v131
	v_cvt_pk_bf16_f32 v131, v136, v137
	global_store_dwordx4 v[164:165], v[128:131], off offset:64 sc1
	s_nop 1
	v_mov_b32_e32 v128, 1.0
	v_mov_b32_e32 v130, 1.0
	s_cbranch_vccnz .LBB0_206
	v_mul_f32_e32 v129, v116, v116
	v_mul_f32_e32 v130, v112, v112
	v_fmac_f32_e32 v129, v117, v117
	v_fmac_f32_e32 v130, v113, v113
	v_fmac_f32_e32 v129, v118, v118
	v_fmac_f32_e32 v130, v114, v114
	v_fmac_f32_e32 v129, v119, v119
	v_fmac_f32_e32 v130, v115, v115
	v_add_f32_e32 v129, v129, v130
	v_mul_f32_e32 v130, v100, v100
	v_mul_f32_e32 v131, v96, v96
	v_fmac_f32_e32 v130, v101, v101
	v_fmac_f32_e32 v131, v97, v97
	v_fmac_f32_e32 v130, v102, v102
	v_fmac_f32_e32 v131, v98, v98
	v_fmac_f32_e32 v130, v103, v103
	v_fmac_f32_e32 v131, v99, v99
	v_add_f32_e32 v130, v130, v131
	v_add_f32_e32 v129, v129, v130
	v_mov_b32_e32 v130, v129
	s_nop 1
	v_permlane16_swap_b32_e32 v129, v130
	v_add_f32_e32 v129, v129, v130
	v_mov_b32_e32 v130, v129
	s_nop 1
	v_permlane32_swap_b32_e32 v129, v130
	v_add_f32_e32 v129, v129, v130
	v_fmamk_f32 v129, v129, 0x3c800000, v174
	v_rsq_f32_e32 v130, v129
.LBB0_206:
	s_nop 0
	v_pk_mul_f32 v[116:117], v[116:117], v[130:131] op_sel_hi:[1,0]
	v_pk_mul_f32 v[114:115], v[114:115], v[130:131] op_sel_hi:[1,0]
	v_pk_mul_f32 v[116:117], v[124:125], v[116:117]
	v_pk_mul_f32 v[112:113], v[112:113], v[130:131] op_sel_hi:[1,0]
	v_pk_mul_f32 v[118:119], v[118:119], v[130:131] op_sel_hi:[1,0]
	v_pk_mul_f32 v[134:135], v[122:123], v[114:115]
	v_pk_mul_f32 v[114:115], v[120:121], v[112:113]
	v_cvt_pk_bf16_f32 v112, v116, v117
	v_add_co_u32_e32 v116, vcc, s75, v164
	v_pk_mul_f32 v[118:119], v[126:127], v[118:119]
	s_nop 0
	v_addc_co_u32_e32 v117, vcc, 0, v165, vcc
	v_cvt_pk_bf16_f32 v113, v118, v119
	v_pk_mul_f32 v[98:99], v[98:99], v[130:131] op_sel_hi:[1,0]
	v_pk_mul_f32 v[96:97], v[96:97], v[130:131] op_sel_hi:[1,0]
	v_lshl_add_u64 v[132:133], v[164:165], 0, s[18:19]
	v_cvt_pk_bf16_f32 v114, v114, v115
	v_cvt_pk_bf16_f32 v115, v134, v135
	global_store_dwordx4 v[116:117], v[112:115], off sc1
	v_pk_mul_f32 v[102:103], v[102:103], v[130:131] op_sel_hi:[1,0]
	v_pk_mul_f32 v[100:101], v[100:101], v[130:131] op_sel_hi:[1,0]
	v_pk_mul_f32 v[112:113], v[106:107], v[98:99]
	v_pk_mul_f32 v[98:99], v[104:105], v[96:97]
	s_and_b64 vcc, exec, s[8:9]
	v_pk_mul_f32 v[102:103], v[110:111], v[102:103]
	v_pk_mul_f32 v[100:101], v[108:109], v[100:101]
	s_nop 0
	v_cvt_pk_bf16_f32 v96, v100, v101
	v_cvt_pk_bf16_f32 v97, v102, v103
	v_cvt_pk_bf16_f32 v98, v98, v99
	v_cvt_pk_bf16_f32 v99, v112, v113
	global_store_dwordx4 v[132:133], v[96:99], off offset:64 sc1
	s_cbranch_vccnz .LBB0_208
	s_nop 0
	v_mul_f32_e32 v96, v92, v92
	v_mul_f32_e32 v97, v88, v88
	v_fmac_f32_e32 v96, v93, v93
	v_fmac_f32_e32 v97, v89, v89
	v_fmac_f32_e32 v96, v94, v94
	v_fmac_f32_e32 v97, v90, v90
	v_fmac_f32_e32 v96, v95, v95
	v_fmac_f32_e32 v97, v91, v91
	v_add_f32_e32 v96, v96, v97
	v_mul_f32_e32 v97, v84, v84
	v_mul_f32_e32 v98, v80, v80
	v_fmac_f32_e32 v97, v85, v85
	v_fmac_f32_e32 v98, v81, v81
	v_fmac_f32_e32 v97, v86, v86
	v_fmac_f32_e32 v98, v82, v82
	v_fmac_f32_e32 v97, v87, v87
	v_fmac_f32_e32 v98, v83, v83
	v_add_f32_e32 v97, v97, v98
	v_add_f32_e32 v96, v96, v97
	v_mov_b32_e32 v97, v96
	s_nop 1
	v_permlane16_swap_b32_e32 v96, v97
	v_add_f32_e32 v96, v96, v97
	v_mov_b32_e32 v97, v96
	s_nop 1
	v_permlane32_swap_b32_e32 v96, v97
	v_add_f32_e32 v96, v96, v97
	v_fmamk_f32 v96, v96, 0x3c800000, v174
	v_rsq_f32_e32 v128, v96
.LBB0_208:
	s_nop 0
	v_pk_mul_f32 v[92:93], v[92:93], v[128:129] op_sel_hi:[1,0]
	v_pk_mul_f32 v[90:91], v[90:91], v[128:129] op_sel_hi:[1,0]
	v_pk_mul_f32 v[92:93], v[124:125], v[92:93]
	v_pk_mul_f32 v[88:89], v[88:89], v[128:129] op_sel_hi:[1,0]
	v_pk_mul_f32 v[94:95], v[94:95], v[128:129] op_sel_hi:[1,0]
	v_pk_mul_f32 v[98:99], v[122:123], v[90:91]
	v_pk_mul_f32 v[90:91], v[120:121], v[88:89]
	v_cvt_pk_bf16_f32 v88, v92, v93
	v_add_co_u32_e32 v92, vcc, s69, v164
	v_pk_mul_f32 v[94:95], v[126:127], v[94:95]
	s_nop 0
	v_addc_co_u32_e32 v93, vcc, 0, v165, vcc
	v_cvt_pk_bf16_f32 v89, v94, v95
	v_pk_mul_f32 v[84:85], v[84:85], v[128:129] op_sel_hi:[1,0]
	v_pk_mul_f32 v[82:83], v[82:83], v[128:129] op_sel_hi:[1,0]
	v_pk_mul_f32 v[80:81], v[80:81], v[128:129] op_sel_hi:[1,0]
	v_lshl_add_u64 v[96:97], v[164:165], 0, s[20:21]
	v_cvt_pk_bf16_f32 v90, v90, v91
	v_cvt_pk_bf16_f32 v91, v98, v99
	global_store_dwordx4 v[92:93], v[88:91], off sc1
	v_pk_mul_f32 v[86:87], v[86:87], v[128:129] op_sel_hi:[1,0]
	v_pk_mul_f32 v[84:85], v[108:109], v[84:85]
	v_pk_mul_f32 v[88:89], v[106:107], v[82:83]
	v_pk_mul_f32 v[82:83], v[104:105], v[80:81]
	v_cvt_pk_bf16_f32 v80, v84, v85
	v_pk_mul_f32 v[86:87], v[110:111], v[86:87]
	s_and_b64 vcc, exec, s[8:9]
	v_cvt_pk_bf16_f32 v81, v86, v87
	v_cvt_pk_bf16_f32 v82, v82, v83
	v_cvt_pk_bf16_f32 v83, v88, v89
	global_store_dwordx4 v[96:97], v[80:83], off offset:64 sc1
	v_mov_b32_e32 v84, 1.0
	s_nop 0
	v_mov_b32_e32 v80, 1.0
	s_cbranch_vccnz .LBB0_210
	v_mul_f32_e32 v81, v76, v76
	v_mul_f32_e32 v82, v72, v72
	v_fmac_f32_e32 v81, v77, v77
	v_fmac_f32_e32 v82, v73, v73
	v_fmac_f32_e32 v81, v78, v78
	v_fmac_f32_e32 v82, v74, v74
	v_fmac_f32_e32 v81, v79, v79
	v_fmac_f32_e32 v82, v75, v75
	v_add_f32_e32 v81, v81, v82
	v_mul_f32_e32 v82, v68, v68
	v_mul_f32_e32 v83, v64, v64
	v_fmac_f32_e32 v82, v69, v69
	v_fmac_f32_e32 v83, v65, v65
	v_fmac_f32_e32 v82, v70, v70
	v_fmac_f32_e32 v83, v66, v66
	v_fmac_f32_e32 v82, v71, v71
	v_fmac_f32_e32 v83, v67, v67
	v_add_f32_e32 v82, v82, v83
	v_add_f32_e32 v81, v81, v82
	v_mov_b32_e32 v82, v81
	s_nop 1
	v_permlane16_swap_b32_e32 v81, v82
	v_add_f32_e32 v81, v81, v82
	v_mov_b32_e32 v82, v81
	s_nop 1
	v_permlane32_swap_b32_e32 v81, v82
	v_add_f32_e32 v81, v81, v82
	v_fmamk_f32 v81, v81, 0x3c800000, v174
	v_rsq_f32_e32 v84, v81
.LBB0_210:
	v_lshlrev_b64 v[82:83], 11, v[160:161]
	v_pk_mul_f32 v[76:77], v[76:77], v[84:85] op_sel_hi:[1,0]
	v_lshl_add_u64 v[82:83], v[162:163], 0, v[82:83]
	v_pk_mul_f32 v[76:77], v[124:125], v[76:77]
	v_pk_mul_f32 v[74:75], v[74:75], v[84:85] op_sel_hi:[1,0]
	v_pk_mul_f32 v[72:73], v[72:73], v[84:85] op_sel_hi:[1,0]
	v_pk_mul_f32 v[78:79], v[78:79], v[84:85] op_sel_hi:[1,0]
	v_pk_mul_f32 v[88:89], v[122:123], v[74:75]
	v_pk_mul_f32 v[74:75], v[120:121], v[72:73]
	v_cvt_pk_bf16_f32 v72, v76, v77
	v_add_co_u32_e32 v76, vcc, s74, v82
	v_pk_mul_f32 v[78:79], v[126:127], v[78:79]
	s_nop 0
	v_addc_co_u32_e32 v77, vcc, 0, v83, vcc
	v_cvt_pk_bf16_f32 v73, v78, v79
	v_pk_mul_f32 v[66:67], v[66:67], v[84:85] op_sel_hi:[1,0]
	v_pk_mul_f32 v[64:65], v[64:65], v[84:85] op_sel_hi:[1,0]
	v_lshl_add_u64 v[86:87], v[82:83], 0, s[22:23]
	v_cvt_pk_bf16_f32 v74, v74, v75
	v_cvt_pk_bf16_f32 v75, v88, v89
	global_store_dwordx4 v[76:77], v[72:75], off sc1
	v_pk_mul_f32 v[70:71], v[70:71], v[84:85] op_sel_hi:[1,0]
	v_pk_mul_f32 v[68:69], v[68:69], v[84:85] op_sel_hi:[1,0]
	v_pk_mul_f32 v[72:73], v[106:107], v[66:67]
	v_pk_mul_f32 v[66:67], v[104:105], v[64:65]
	s_and_b64 vcc, exec, s[8:9]
	v_pk_mul_f32 v[70:71], v[110:111], v[70:71]
	v_pk_mul_f32 v[68:69], v[108:109], v[68:69]
	s_nop 0
	v_cvt_pk_bf16_f32 v64, v68, v69
	v_cvt_pk_bf16_f32 v65, v70, v71
	v_cvt_pk_bf16_f32 v66, v66, v67
	v_cvt_pk_bf16_f32 v67, v72, v73
	global_store_dwordx4 v[86:87], v[64:67], off offset:64 sc1
	s_cbranch_vccnz .LBB0_212
	s_nop 0
	v_mul_f32_e32 v64, v60, v60
	v_mul_f32_e32 v65, v56, v56
	v_fmac_f32_e32 v64, v61, v61
	v_fmac_f32_e32 v65, v57, v57
	v_fmac_f32_e32 v64, v62, v62
	v_fmac_f32_e32 v65, v58, v58
	v_fmac_f32_e32 v64, v63, v63
	v_fmac_f32_e32 v65, v59, v59
	v_add_f32_e32 v64, v64, v65
	v_mul_f32_e32 v65, v52, v52
	v_mul_f32_e32 v66, v48, v48
	v_fmac_f32_e32 v65, v53, v53
	v_fmac_f32_e32 v66, v49, v49
	v_fmac_f32_e32 v65, v54, v54
	v_fmac_f32_e32 v66, v50, v50
	v_fmac_f32_e32 v65, v55, v55
	v_fmac_f32_e32 v66, v51, v51
	v_add_f32_e32 v65, v65, v66
	v_add_f32_e32 v64, v64, v65
	v_mov_b32_e32 v65, v64
	s_nop 1
	v_permlane16_swap_b32_e32 v64, v65
	v_add_f32_e32 v64, v64, v65
	v_mov_b32_e32 v65, v64
	s_nop 1
	v_permlane32_swap_b32_e32 v64, v65
	v_add_f32_e32 v64, v64, v65
	v_fmamk_f32 v64, v64, 0x3c800000, v174
	v_rsq_f32_e32 v80, v64
.LBB0_212:
	s_nop 0
	v_pk_mul_f32 v[60:61], v[60:61], v[80:81] op_sel_hi:[1,0]
	v_pk_mul_f32 v[58:59], v[58:59], v[80:81] op_sel_hi:[1,0]
	v_pk_mul_f32 v[60:61], v[124:125], v[60:61]
	v_pk_mul_f32 v[56:57], v[56:57], v[80:81] op_sel_hi:[1,0]
	v_pk_mul_f32 v[62:63], v[62:63], v[80:81] op_sel_hi:[1,0]
	v_pk_mul_f32 v[66:67], v[122:123], v[58:59]
	v_pk_mul_f32 v[58:59], v[120:121], v[56:57]
	v_cvt_pk_bf16_f32 v56, v60, v61
	v_add_co_u32_e32 v60, vcc, s82, v82
	v_pk_mul_f32 v[62:63], v[126:127], v[62:63]
	s_nop 0
	v_addc_co_u32_e32 v61, vcc, 0, v83, vcc
	v_cvt_pk_bf16_f32 v57, v62, v63
	v_pk_mul_f32 v[52:53], v[52:53], v[80:81] op_sel_hi:[1,0]
	v_pk_mul_f32 v[50:51], v[50:51], v[80:81] op_sel_hi:[1,0]
	v_pk_mul_f32 v[48:49], v[48:49], v[80:81] op_sel_hi:[1,0]
	v_lshl_add_u64 v[64:65], v[82:83], 0, s[10:11]
	v_cvt_pk_bf16_f32 v58, v58, v59
	v_cvt_pk_bf16_f32 v59, v66, v67
	global_store_dwordx4 v[60:61], v[56:59], off sc1
	v_pk_mul_f32 v[54:55], v[54:55], v[80:81] op_sel_hi:[1,0]
	v_pk_mul_f32 v[52:53], v[108:109], v[52:53]
	v_pk_mul_f32 v[56:57], v[106:107], v[50:51]
	v_pk_mul_f32 v[50:51], v[104:105], v[48:49]
	v_cvt_pk_bf16_f32 v48, v52, v53
	v_pk_mul_f32 v[54:55], v[110:111], v[54:55]
	s_and_b64 vcc, exec, s[8:9]
	v_cvt_pk_bf16_f32 v49, v54, v55
	v_cvt_pk_bf16_f32 v50, v50, v51
	v_cvt_pk_bf16_f32 v51, v56, v57
	global_store_dwordx4 v[64:65], v[48:51], off offset:64 sc1
	v_mov_b32_e32 v52, 1.0
	s_nop 0
	v_mov_b32_e32 v48, 1.0
	s_cbranch_vccnz .LBB0_214
	v_mul_f32_e32 v49, v44, v44
	v_mul_f32_e32 v50, v40, v40
	v_fmac_f32_e32 v49, v45, v45
	v_fmac_f32_e32 v50, v41, v41
	v_fmac_f32_e32 v49, v46, v46
	v_fmac_f32_e32 v50, v42, v42
	v_fmac_f32_e32 v49, v47, v47
	v_fmac_f32_e32 v50, v43, v43
	v_add_f32_e32 v49, v49, v50
	v_mul_f32_e32 v50, v36, v36
	v_mul_f32_e32 v51, v32, v32
	v_fmac_f32_e32 v50, v37, v37
	v_fmac_f32_e32 v51, v33, v33
	v_fmac_f32_e32 v50, v38, v38
	v_fmac_f32_e32 v51, v34, v34
	v_fmac_f32_e32 v50, v39, v39
	v_fmac_f32_e32 v51, v35, v35
	v_add_f32_e32 v50, v50, v51
	v_add_f32_e32 v49, v49, v50
	v_mov_b32_e32 v50, v49
	s_nop 1
	v_permlane16_swap_b32_e32 v49, v50
	v_add_f32_e32 v49, v49, v50
	v_mov_b32_e32 v50, v49
	s_nop 1
	v_permlane32_swap_b32_e32 v49, v50
	v_add_f32_e32 v49, v49, v50
	v_fmamk_f32 v49, v49, 0x3c800000, v174
	v_rsq_f32_e32 v52, v49
.LBB0_214:
	v_lshlrev_b64 v[50:51], 11, v[160:161]
	v_pk_mul_f32 v[44:45], v[44:45], v[52:53] op_sel_hi:[1,0]
	v_lshl_add_u64 v[50:51], v[162:163], 0, v[50:51]
	v_pk_mul_f32 v[44:45], v[124:125], v[44:45]
	v_pk_mul_f32 v[42:43], v[42:43], v[52:53] op_sel_hi:[1,0]
	v_pk_mul_f32 v[40:41], v[40:41], v[52:53] op_sel_hi:[1,0]
	v_pk_mul_f32 v[46:47], v[46:47], v[52:53] op_sel_hi:[1,0]
	v_pk_mul_f32 v[56:57], v[122:123], v[42:43]
	v_pk_mul_f32 v[42:43], v[120:121], v[40:41]
	v_cvt_pk_bf16_f32 v40, v44, v45
	v_add_co_u32_e32 v44, vcc, s83, v50
	v_pk_mul_f32 v[46:47], v[126:127], v[46:47]
	s_nop 0
	v_addc_co_u32_e32 v45, vcc, 0, v51, vcc
	v_cvt_pk_bf16_f32 v41, v46, v47
	v_pk_mul_f32 v[34:35], v[34:35], v[52:53] op_sel_hi:[1,0]
	v_pk_mul_f32 v[32:33], v[32:33], v[52:53] op_sel_hi:[1,0]
	v_lshl_add_u64 v[54:55], v[50:51], 0, s[24:25]
	v_cvt_pk_bf16_f32 v42, v42, v43
	v_cvt_pk_bf16_f32 v43, v56, v57
	global_store_dwordx4 v[44:45], v[40:43], off sc1
	v_pk_mul_f32 v[38:39], v[38:39], v[52:53] op_sel_hi:[1,0]
	v_pk_mul_f32 v[36:37], v[36:37], v[52:53] op_sel_hi:[1,0]
	v_pk_mul_f32 v[40:41], v[106:107], v[34:35]
	v_pk_mul_f32 v[34:35], v[104:105], v[32:33]
	s_and_b64 vcc, exec, s[8:9]
	v_pk_mul_f32 v[38:39], v[110:111], v[38:39]
	v_pk_mul_f32 v[36:37], v[108:109], v[36:37]
	s_nop 0
	v_cvt_pk_bf16_f32 v32, v36, v37
	v_cvt_pk_bf16_f32 v33, v38, v39
	v_cvt_pk_bf16_f32 v34, v34, v35
	v_cvt_pk_bf16_f32 v35, v40, v41
	global_store_dwordx4 v[54:55], v[32:35], off offset:64 sc1
	s_cbranch_vccnz .LBB0_216
	s_nop 0
	v_mul_f32_e32 v32, v28, v28
	v_mul_f32_e32 v33, v24, v24
	v_fmac_f32_e32 v32, v29, v29
	v_fmac_f32_e32 v33, v25, v25
	v_fmac_f32_e32 v32, v30, v30
	v_fmac_f32_e32 v33, v26, v26
	v_fmac_f32_e32 v32, v31, v31
	v_fmac_f32_e32 v33, v27, v27
	v_add_f32_e32 v32, v32, v33
	v_mul_f32_e32 v33, v20, v20
	v_mul_f32_e32 v34, v16, v16
	v_fmac_f32_e32 v33, v21, v21
	v_fmac_f32_e32 v34, v17, v17
	v_fmac_f32_e32 v33, v22, v22
	v_fmac_f32_e32 v34, v18, v18
	v_fmac_f32_e32 v33, v23, v23
	v_fmac_f32_e32 v34, v19, v19
	v_add_f32_e32 v33, v33, v34
	v_add_f32_e32 v32, v32, v33
	v_mov_b32_e32 v33, v32
	s_nop 1
	v_permlane16_swap_b32_e32 v32, v33
	v_add_f32_e32 v32, v32, v33
	v_mov_b32_e32 v33, v32
	s_nop 1
	v_permlane32_swap_b32_e32 v32, v33
	v_add_f32_e32 v32, v32, v33
	v_fmamk_f32 v32, v32, 0x3c800000, v174
	v_rsq_f32_e32 v48, v32
.LBB0_216:
	s_nop 0
	v_pk_mul_f32 v[28:29], v[28:29], v[48:49] op_sel_hi:[1,0]
	v_pk_mul_f32 v[26:27], v[26:27], v[48:49] op_sel_hi:[1,0]
	v_pk_mul_f32 v[28:29], v[124:125], v[28:29]
	v_pk_mul_f32 v[24:25], v[24:25], v[48:49] op_sel_hi:[1,0]
	v_pk_mul_f32 v[30:31], v[30:31], v[48:49] op_sel_hi:[1,0]
	v_pk_mul_f32 v[34:35], v[122:123], v[26:27]
	v_pk_mul_f32 v[26:27], v[120:121], v[24:25]
	v_cvt_pk_bf16_f32 v24, v28, v29
	v_add_co_u32_e32 v28, vcc, s84, v50
	v_pk_mul_f32 v[30:31], v[126:127], v[30:31]
	s_nop 0
	v_addc_co_u32_e32 v29, vcc, 0, v51, vcc
	v_cvt_pk_bf16_f32 v25, v30, v31
	v_pk_mul_f32 v[20:21], v[20:21], v[48:49] op_sel_hi:[1,0]
	v_pk_mul_f32 v[18:19], v[18:19], v[48:49] op_sel_hi:[1,0]
	v_pk_mul_f32 v[16:17], v[16:17], v[48:49] op_sel_hi:[1,0]
	v_lshl_add_u64 v[32:33], v[50:51], 0, s[38:39]
	v_cvt_pk_bf16_f32 v26, v26, v27
	v_cvt_pk_bf16_f32 v27, v34, v35
	global_store_dwordx4 v[28:29], v[24:27], off sc1
	v_pk_mul_f32 v[22:23], v[22:23], v[48:49] op_sel_hi:[1,0]
	v_pk_mul_f32 v[20:21], v[108:109], v[20:21]
	v_pk_mul_f32 v[24:25], v[106:107], v[18:19]
	v_pk_mul_f32 v[18:19], v[104:105], v[16:17]
	v_cvt_pk_bf16_f32 v16, v20, v21
	v_pk_mul_f32 v[22:23], v[110:111], v[22:23]
	s_and_b64 vcc, exec, s[8:9]
	v_cvt_pk_bf16_f32 v17, v22, v23
	v_cvt_pk_bf16_f32 v18, v18, v19
	v_cvt_pk_bf16_f32 v19, v24, v25
	global_store_dwordx4 v[32:33], v[16:19], off offset:64 sc1
	s_nop 1
	v_mov_b32_e32 v16, 1.0
	s_cbranch_vccnz .LBB0_218
	v_mul_f32_e32 v16, v12, v12
	v_mul_f32_e32 v17, v8, v8
	v_fmac_f32_e32 v16, v13, v13
	v_fmac_f32_e32 v17, v9, v9
	v_fmac_f32_e32 v16, v14, v14
	v_fmac_f32_e32 v17, v10, v10
	v_fmac_f32_e32 v16, v15, v15
	v_fmac_f32_e32 v17, v11, v11
	v_add_f32_e32 v16, v16, v17
	v_mul_f32_e32 v17, v4, v4
	v_mul_f32_e32 v18, v0, v0
	v_fmac_f32_e32 v17, v5, v5
	v_fmac_f32_e32 v18, v1, v1
	v_fmac_f32_e32 v17, v6, v6
	v_fmac_f32_e32 v18, v2, v2
	v_fmac_f32_e32 v17, v7, v7
	v_fmac_f32_e32 v18, v3, v3
	v_add_f32_e32 v17, v17, v18
	v_add_f32_e32 v16, v16, v17
	v_mov_b32_e32 v17, v16
	s_nop 1
	v_permlane16_swap_b32_e32 v16, v17
	v_add_f32_e32 v16, v16, v17
	v_mov_b32_e32 v17, v16
	s_nop 1
	v_permlane32_swap_b32_e32 v16, v17
	v_add_f32_e32 v16, v16, v17
	v_fmamk_f32 v16, v16, 0x3c800000, v174
	v_rsq_f32_e32 v16, v16
.LBB0_218:
	v_lshlrev_b64 v[18:19], 11, v[160:161]
	v_pk_mul_f32 v[12:13], v[12:13], v[16:17] op_sel_hi:[1,0]
	v_lshl_add_u64 v[18:19], v[162:163], 0, v[18:19]
	v_pk_mul_f32 v[12:13], v[124:125], v[12:13]
	v_pk_mul_f32 v[10:11], v[10:11], v[16:17] op_sel_hi:[1,0]
	v_pk_mul_f32 v[8:9], v[8:9], v[16:17] op_sel_hi:[1,0]
	v_pk_mul_f32 v[14:15], v[14:15], v[16:17] op_sel_hi:[1,0]
	v_pk_mul_f32 v[22:23], v[122:123], v[10:11]
	v_pk_mul_f32 v[10:11], v[120:121], v[8:9]
	v_cvt_pk_bf16_f32 v8, v12, v13
	v_add_co_u32_e32 v12, vcc, s85, v18
	v_pk_mul_f32 v[14:15], v[126:127], v[14:15]
	s_nop 0
	v_addc_co_u32_e32 v13, vcc, 0, v19, vcc
	v_cvt_pk_bf16_f32 v9, v14, v15
	v_pk_mul_f32 v[2:3], v[2:3], v[16:17] op_sel_hi:[1,0]
	v_pk_mul_f32 v[0:1], v[0:1], v[16:17] op_sel_hi:[1,0]
	v_lshl_add_u64 v[20:21], v[18:19], 0, s[40:41]
	v_cvt_pk_bf16_f32 v10, v10, v11
	v_cvt_pk_bf16_f32 v11, v22, v23
	global_store_dwordx4 v[12:13], v[8:11], off sc1
	v_pk_mul_f32 v[6:7], v[6:7], v[16:17] op_sel_hi:[1,0]
	v_pk_mul_f32 v[4:5], v[4:5], v[16:17] op_sel_hi:[1,0]
	v_pk_mul_f32 v[8:9], v[106:107], v[2:3]
	v_pk_mul_f32 v[2:3], v[104:105], v[0:1]
	s_andn2_b64 vcc, exec, s[6:7]
	s_mov_b64 s[6:7], -1
	v_pk_mul_f32 v[6:7], v[110:111], v[6:7]
	v_pk_mul_f32 v[4:5], v[108:109], v[4:5]
	s_nop 0
	v_cvt_pk_bf16_f32 v0, v4, v5
	v_cvt_pk_bf16_f32 v1, v6, v7
	v_cvt_pk_bf16_f32 v2, v2, v3
	v_cvt_pk_bf16_f32 v3, v8, v9
	global_store_dwordx4 v[20:21], v[0:3], off offset:64 sc1
	s_cbranch_vccnz .LBB0_193
	s_andn2_b64 vcc, exec, s[12:13]
	s_cbranch_vccnz .LBB0_192
	s_barrier
	s_branch .LBB0_192

.Lattn_tk_skip:
	s_or_b64 exec, exec, s[98:99]
	s_waitcnt lgkmcnt(0)
	ds_read_b128 v[2:5], v213 offset:49280
	ds_read_b128 v[6:9], v213 offset:49312
	s_lshl_b64 s[6:7], s[52:53], 1
	s_add_u32 s6, s75, s6
	s_addc_u32 s7, s76, s7
	s_waitcnt lgkmcnt(1)
	v_rcp_f32_e32 v0, v2
	v_rcp_f32_e32 v10, v3
	s_lshl_b32 s8, s62, 12
	s_add_i32 s8, s8, 0
	v_lshlrev_b32_e32 v49, 1, v206
	v_lshlrev_b32_e32 v50, 9, v207
	v_mul_f32_e32 v32, v32, v0
	v_mul_f32_e32 v0, v16, v0
	v_add3_u32 v49, s8, v49, v50
	v_cvt_pk_bf16_f32 v0, v0, s0
	v_rcp_f32_e32 v11, v4
	v_rcp_f32_e32 v12, v5
	s_waitcnt lgkmcnt(0)
	v_rcp_f32_e32 v13, v6
	ds_read_b128 v[2:5], v213 offset:49344
	v_rcp_f32_e32 v14, v7
	v_rcp_f32_e32 v15, v8
	v_rcp_f32_e32 v48, v9
	ds_read_b128 v[6:9], v213 offset:49376
	ds_write_b16 v49, v0 offset:51264
	v_mul_f32_e32 v0, v33, v10
	v_cvt_pk_bf16_f32 v0, v0, s0
	ds_write_b16 v49, v0 offset:51328
	v_mul_f32_e32 v0, v17, v10
	v_cvt_pk_bf16_f32 v0, v0, s0
	ds_write_b16 v49, v0 offset:51392
	v_mul_f32_e32 v0, v34, v11
	v_cvt_pk_bf16_f32 v0, v0, s0
	ds_write_b16 v49, v0 offset:51456
	v_mul_f32_e32 v0, v18, v11
	v_cvt_pk_bf16_f32 v0, v0, s0
	ds_write_b16 v49, v0 offset:51520
	v_mul_f32_e32 v0, v35, v12
	v_cvt_pk_bf16_f32 v0, v0, s0
	ds_write_b16 v49, v0 offset:51584
	v_mul_f32_e32 v0, v19, v12
	v_cvt_pk_bf16_f32 v0, v0, s0
	ds_write_b16 v49, v0 offset:51648
	v_mul_f32_e32 v0, v36, v13
	v_cvt_pk_bf16_f32 v0, v0, s0
	ds_write_b16 v49, v0 offset:52224
	v_mul_f32_e32 v0, v20, v13
	v_cvt_pk_bf16_f32 v0, v0, s0
	ds_write_b16 v49, v0 offset:52288
	v_mul_f32_e32 v0, v37, v14
	v_cvt_pk_bf16_f32 v0, v0, s0
	ds_write_b16 v49, v0 offset:52352
	v_mul_f32_e32 v0, v21, v14
	v_cvt_pk_bf16_f32 v0, v0, s0
	ds_write_b16 v49, v0 offset:52416
	v_mul_f32_e32 v0, v38, v15
	v_cvt_pk_bf16_f32 v0, v0, s0
	ds_write_b16 v49, v0 offset:52480
	v_mul_f32_e32 v0, v22, v15
	v_cvt_pk_bf16_f32 v0, v0, s0
	s_waitcnt lgkmcnt(13)
	v_rcp_f32_e32 v2, v2
	ds_write_b16 v49, v0 offset:52544
	v_mul_f32_e32 v0, v39, v48
	v_cvt_pk_bf16_f32 v0, v0, s0
	ds_write_b16 v49, v0 offset:52608
	v_mul_f32_e32 v0, v23, v48
	v_cvt_pk_bf16_f32 v0, v0, s0
	v_rcp_f32_e32 v3, v3
	ds_write_b16 v49, v0 offset:52672
	v_mul_f32_e32 v0, v40, v2
	v_cvt_pk_bf16_f32 v0, v0, s0
	ds_write_b16 v49, v0 offset:53248
	v_mul_f32_e32 v0, v24, v2
	v_cvt_pk_bf16_f32 v0, v0, s0
	v_rcp_f32_e32 v4, v4
	ds_write_b16 v49, v0 offset:53312
	v_mul_f32_e32 v0, v41, v3
	v_cvt_pk_bf16_f32 v0, v0, s0
	ds_write_b16 v49, v0 offset:53376
	v_mul_f32_e32 v0, v25, v3
	v_cvt_pk_bf16_f32 v0, v0, s0
	v_rcp_f32_e32 v5, v5
	ds_write_b16 v49, v0 offset:53440
	v_mul_f32_e32 v0, v42, v4
	v_cvt_pk_bf16_f32 v0, v0, s0
	ds_write_b16 v49, v0 offset:53504
	v_mul_f32_e32 v0, v26, v4
	v_cvt_pk_bf16_f32 v0, v0, s0
	s_waitcnt lgkmcnt(14)
	v_rcp_f32_e32 v6, v6
	ds_write_b16 v49, v0 offset:53568
	v_mul_f32_e32 v0, v43, v5
	v_cvt_pk_bf16_f32 v0, v0, s0
	ds_write_b16 v49, v0 offset:53632
	v_mul_f32_e32 v0, v27, v5
	v_cvt_pk_bf16_f32 v0, v0, s0
	v_rcp_f32_e32 v7, v7
	ds_write_b16 v49, v0 offset:53696
	v_mul_f32_e32 v0, v44, v6
	v_cvt_pk_bf16_f32 v0, v0, s0
	ds_write_b16 v49, v0 offset:54272
	v_mul_f32_e32 v0, v28, v6
	v_cvt_pk_bf16_f32 v0, v0, s0
	v_rcp_f32_e32 v8, v8
	ds_write_b16 v49, v0 offset:54336
	v_mul_f32_e32 v0, v45, v7
	v_cvt_pk_bf16_f32 v0, v0, s0
	ds_write_b16 v49, v0 offset:54400
	v_mul_f32_e32 v0, v29, v7
	v_cvt_pk_bf16_f32 v0, v0, s0
	v_rcp_f32_e32 v9, v9
	ds_write_b16 v49, v0 offset:54464
	v_mul_f32_e32 v0, v46, v8
	v_cvt_pk_bf16_f32 v0, v0, s0
	ds_write_b16 v49, v0 offset:54528
	v_mul_f32_e32 v0, v30, v8
	v_cvt_pk_bf16_f32 v0, v0, s0
	ds_write_b16 v49, v0 offset:54592
	v_mul_f32_e32 v0, v47, v9
	v_cvt_pk_bf16_f32 v0, v0, s0
	ds_write_b16 v49, v0 offset:54656
	v_mul_f32_e32 v0, v31, v9
	v_cvt_pk_bf16_f32 v0, v0, s0
	ds_write_b16 v49, v0 offset:54720
	v_lshlrev_b32_e32 v0, 1, v205
	v_cvt_pk_bf16_f32 v32, v32, s0
	s_add_u32 s6, s6, s63
	v_and_b32_e32 v0, 0x70, v0
	ds_write_b16 v49, v32 offset:51200
	s_addc_u32 s7, s7, 0
	v_lshrrev_b32_e32 v14, 3, v204
	v_add_u32_e32 v15, s8, v0
	s_waitcnt lgkmcnt(0)
	v_lshl_add_u64 v[10:11], s[6:7], 0, v[0:1]
	v_lshl_add_u32 v0, v14, 7, v15
	v_or_b32_e32 v16, 8, v14
	ds_read_b128 v[2:5], v0 offset:51200
	v_lshl_add_u32 v6, v16, 7, v15
	ds_read_b128 v[6:9], v6 offset:51200
	v_lshlrev_b32_e32 v0, 11, v14
	v_lshl_add_u64 v[12:13], v[10:11], 0, v[0:1]
	v_lshlrev_b32_e32 v0, 11, v16
	s_waitcnt lgkmcnt(1)
	global_store_dwordx4 v[12:13], v[2:5], off sc1
	s_nop 1
	v_lshl_add_u64 v[2:3], v[10:11], 0, v[0:1]
	v_or_b32_e32 v0, 16, v14
	s_waitcnt lgkmcnt(0)
	global_store_dwordx4 v[2:3], v[6:9], off sc1
	v_lshl_add_u32 v2, v0, 7, v15
	v_or_b32_e32 v14, 24, v14
	ds_read_b128 v[2:5], v2 offset:51200
	v_lshl_add_u32 v6, v14, 7, v15
	ds_read_b128 v[6:9], v6 offset:51200
	v_lshlrev_b32_e32 v0, 11, v0
	v_lshl_add_u64 v[12:13], v[10:11], 0, v[0:1]
	v_lshlrev_b32_e32 v0, 11, v14
	s_waitcnt lgkmcnt(1)
	global_store_dwordx4 v[12:13], v[2:5], off sc1
	s_nop 1
	v_lshl_add_u64 v[2:3], v[10:11], 0, v[0:1]
	s_waitcnt lgkmcnt(0)
	global_store_dwordx4 v[2:3], v[6:9], off sc1
	s_waitcnt lgkmcnt(0)
	s_barrier
	v_mov_b32_e32 v2, v203
	v_mov_b32_e32 v203, -1
	s_and_saveexec_b64 s[6:7], s[26:27]
	s_cbranch_execz .LBB0_352
	s_mov_b64 s[52:53], exec
	v_mbcnt_lo_u32_b32 v0, s52, 0
	v_mbcnt_hi_u32_b32 v0, s53, v0
	v_cmp_eq_u32_e32 vcc, 0, v0
	s_and_saveexec_b64 s[8:9], vcc
	s_cbranch_execz .LBB0_321
	s_nop 0
	s_nop 0
	s_nop 0

.LBB0_464:
	v_mov_b64_e32 v[54:55], v[4:5]
	s_cmp_eq_u32 s4, 5
	v_mov_b64_e32 v[52:53], v[2:3]
	v_cvt_f32_f64_e32 v4, v[54:55]
	v_mov_b64_e32 v[50:51], v[0:1]
	v_cvt_f32_f64_e32 v5, v[6:7]
	s_cselect_b64 vcc, -1, 0
	v_cndmask_b32_e32 v1, v1, v5, vcc
	v_cndmask_b32_e32 v0, v0, v4, vcc
	v_mul_f64 v[4:5], v[6:7], v[6:7]
	v_add_f64 v[50:51], v[54:55], v[54:55]
	s_add_i32 s4, s4, -1
	v_cndmask_b32_e32 v3, v3, v53, vcc
	v_cndmask_b32_e32 v2, v2, v52, vcc
	v_fma_f64 v[4:5], v[54:55], v[54:55], -v[4:5]
	s_cmp_eq_u32 s4, 0
	v_mul_f64 v[6:7], v[6:7], v[50:51]
	s_cbranch_scc0 .LBB0_464
	v_cvt_f32_f64_e32 v2, v[4:5]
	v_cvt_f32_f64_e32 v3, v[6:7]
	v_lshl_add_u64 v[4:5], v[48:49], 4, s[40:41]
	global_store_dwordx4 v[4:5], v[0:3], off sc1

.LBB0_492:
	s_or_b64 exec, exec, s[4:5]
	s_waitcnt lgkmcnt(0)
	v_cvt_pk_bf16_f32 v52, v7, v6
	v_add_u32_e32 v5, s87, v5
	v_mov_b64_e32 v[6:7], s[38:39]
	v_cvt_pk_bf16_f32 v53, v37, v8
	v_mad_i64_i32 v[6:7], s[4:5], v5, s96, v[6:7]
	v_lshlrev_b32_e32 v8, 1, v4
	s_addk_i32 s91, 0x200
	v_lshl_add_u64 v[4:5], v[6:7], 0, v[8:9]
	s_cmpk_lg_i32 s91, 0xc00
	v_cvt_pk_bf16_f32 v54, v48, v44
	v_cvt_pk_bf16_f32 v55, v49, v50
	global_store_dwordx4 v[4:5], v[52:55], off sc1
	s_cbranch_scc0 .LBB0_512

.LBB0_513:
	s_or_b64 exec, exec, s[4:5]
	v_cvt_pk_bf16_f32 v52, v6, v7
	v_add_u32_e32 v6, s82, v5
	v_ashrrev_i32_e32 v7, 31, v6
	v_lshlrev_b64 v[6:7], 9, v[6:7]
	s_add_i32 s82, s82, 16
	v_lshl_add_u64 v[6:7], v[10:11], 0, v[6:7]
	s_cmp_eq_u32 s82, 64
	v_cvt_pk_bf16_f32 v53, v37, v44
	v_cvt_pk_bf16_f32 v54, v48, v49
	v_cvt_pk_bf16_f32 v55, v50, v51
	global_store_dwordx4 v[6:7], v[52:55], off sc1
	s_cbranch_scc1 .LBB0_448

.LBB0_905:
	s_lshl_b32 s17, s24, 8
	s_add_i32 s17, s17, s52
	v_or_b32_e32 v146, s17, v150
	v_ashrrev_i32_e32 v147, 31, v146
	v_lshl_add_u64 v[148:149], v[146:147], 2, s[10:11]
	global_load_dword v246, v[148:149], off
	global_load_dword v247, v[148:149], off offset:64
	global_load_dword v248, v[148:149], off offset:128
	global_load_dword v249, v[148:149], off offset:192
	global_load_dword v250, v[148:149], off offset:512
	global_load_dword v251, v[148:149], off offset:576
	global_load_dword v252, v[148:149], off offset:640
	global_load_dword v253, v[148:149], off offset:704
	s_nop 0
	s_lshl_b32 s19, s60, 14
	v_bitop3_b32 v147, s19, v157, v156 bitop3:0xc8
	s_ashr_i32 s17, s17, 4
	v_or_b32_e32 v158, 0x2000, v147
	v_add_u32_e32 v161, s17, v147
	v_add_u32_e32 v165, s17, v158
	v_or_b32_e32 v160, 16, v146
	v_mad_i64_i32 v[162:163], s[36:37], v161, s59, v[136:137]
	v_mad_i64_i32 v[166:167], s[36:37], v165, s59, v[136:137]
	v_ashrrev_i32_e32 v161, 31, v160
	v_lshl_add_u64 v[168:169], v[160:161], 2, s[10:11]
	s_andn2_b64 vcc, exec, s[4:5]
	s_waitcnt vmcnt(0)
	v_mov_b32_e32 v159, v246
	v_fmamk_f32 v159, v159, 0x3a800000, v155
	v_rsq_f32_e32 v164, v159
	s_nop 0
	v_pk_mul_f32 v[126:127], v[126:127], v[164:165] op_sel_hi:[1,0]
	v_pk_mul_f32 v[124:125], v[124:125], v[164:165] op_sel_hi:[1,0]
	v_pk_mul_f32 v[122:123], v[122:123], v[164:165] op_sel_hi:[1,0]
	v_pk_mul_f32 v[120:121], v[120:121], v[164:165] op_sel_hi:[1,0]
	v_pk_mul_f32 v[118:119], v[118:119], v[164:165] op_sel_hi:[1,0]
	v_pk_mul_f32 v[116:117], v[116:117], v[164:165] op_sel_hi:[1,0]
	v_pk_mul_f32 v[170:171], v[114:115], v[164:165] op_sel_hi:[1,0]
	v_pk_mul_f32 v[164:165], v[112:113], v[164:165] op_sel_hi:[1,0]
	v_cvt_pk_bf16_f32 v112, v124, v125
	v_cvt_pk_bf16_f32 v113, v126, v127
	v_cvt_pk_bf16_f32 v114, v120, v121
	v_cvt_pk_bf16_f32 v115, v122, v123
	global_store_dwordx4 v[162:163], v[112:115], off sc1
	s_nop 1
	v_cvt_pk_bf16_f32 v112, v116, v117
	v_cvt_pk_bf16_f32 v113, v118, v119
	v_cvt_pk_bf16_f32 v114, v164, v165
	v_cvt_pk_bf16_f32 v115, v170, v171
	global_store_dwordx4 v[166:167], v[112:115], off sc1
	s_nop 0
	s_nop 0
	v_or_b32_e32 v112, 32, v146
	v_ashrrev_i32_e32 v114, 4, v160
	v_ashrrev_i32_e32 v113, 31, v112
	v_add_u32_e32 v117, v114, v147
	v_add_u32_e32 v120, v158, v114
	v_lshl_add_u64 v[114:115], v[112:113], 2, s[10:11]
	v_mad_i64_i32 v[118:119], s[36:37], v117, s59, v[136:137]
	v_mad_i64_i32 v[120:121], s[36:37], v120, s59, v[136:137]
	v_mov_b32_e32 v116, v247
	v_fmamk_f32 v113, v116, 0x3a800000, v155
	v_rsq_f32_e32 v116, v113
	s_nop 0
	v_pk_mul_f32 v[110:111], v[110:111], v[116:117] op_sel_hi:[1,0]
	v_pk_mul_f32 v[108:109], v[108:109], v[116:117] op_sel_hi:[1,0]
	v_pk_mul_f32 v[106:107], v[106:107], v[116:117] op_sel_hi:[1,0]
	v_pk_mul_f32 v[104:105], v[104:105], v[116:117] op_sel_hi:[1,0]
	v_pk_mul_f32 v[102:103], v[102:103], v[116:117] op_sel_hi:[1,0]
	v_pk_mul_f32 v[100:101], v[100:101], v[116:117] op_sel_hi:[1,0]
	v_pk_mul_f32 v[122:123], v[98:99], v[116:117] op_sel_hi:[1,0]
	v_pk_mul_f32 v[116:117], v[96:97], v[116:117] op_sel_hi:[1,0]
	v_cvt_pk_bf16_f32 v96, v108, v109
	v_cvt_pk_bf16_f32 v97, v110, v111
	v_cvt_pk_bf16_f32 v98, v104, v105
	v_cvt_pk_bf16_f32 v99, v106, v107
	global_store_dwordx4 v[118:119], v[96:99], off sc1
	s_nop 1
	v_cvt_pk_bf16_f32 v96, v100, v101
	v_cvt_pk_bf16_f32 v97, v102, v103
	v_cvt_pk_bf16_f32 v98, v116, v117
	v_cvt_pk_bf16_f32 v99, v122, v123
	global_store_dwordx4 v[120:121], v[96:99], off sc1
	s_nop 0
	s_nop 0
	v_or_b32_e32 v96, 48, v146
	v_ashrrev_i32_e32 v98, 4, v112
	v_ashrrev_i32_e32 v97, 31, v96
	v_add_u32_e32 v101, v98, v147
	v_add_u32_e32 v104, v158, v98
	v_lshl_add_u64 v[98:99], v[96:97], 2, s[10:11]
	v_mad_i64_i32 v[102:103], s[36:37], v101, s59, v[136:137]
	v_mad_i64_i32 v[104:105], s[36:37], v104, s59, v[136:137]
	v_mov_b32_e32 v100, v248
	v_fmamk_f32 v97, v100, 0x3a800000, v155
	v_rsq_f32_e32 v100, v97
	s_nop 0
	v_pk_mul_f32 v[94:95], v[94:95], v[100:101] op_sel_hi:[1,0]
	v_pk_mul_f32 v[92:93], v[92:93], v[100:101] op_sel_hi:[1,0]
	v_pk_mul_f32 v[90:91], v[90:91], v[100:101] op_sel_hi:[1,0]
	v_pk_mul_f32 v[88:89], v[88:89], v[100:101] op_sel_hi:[1,0]
	v_pk_mul_f32 v[86:87], v[86:87], v[100:101] op_sel_hi:[1,0]
	v_pk_mul_f32 v[84:85], v[84:85], v[100:101] op_sel_hi:[1,0]
	v_pk_mul_f32 v[106:107], v[82:83], v[100:101] op_sel_hi:[1,0]
	v_pk_mul_f32 v[100:101], v[80:81], v[100:101] op_sel_hi:[1,0]
	v_cvt_pk_bf16_f32 v80, v92, v93
	v_cvt_pk_bf16_f32 v81, v94, v95
	v_cvt_pk_bf16_f32 v82, v88, v89
	v_cvt_pk_bf16_f32 v83, v90, v91
	global_store_dwordx4 v[102:103], v[80:83], off sc1
	s_nop 1
	v_cvt_pk_bf16_f32 v80, v84, v85
	v_cvt_pk_bf16_f32 v81, v86, v87
	v_cvt_pk_bf16_f32 v82, v100, v101
	v_cvt_pk_bf16_f32 v83, v106, v107
	global_store_dwordx4 v[104:105], v[80:83], off sc1
	s_nop 0
	s_nop 0
	v_ashrrev_i32_e32 v81, 4, v96
	v_add_u32_e32 v82, v81, v147
	v_add_u32_e32 v81, v158, v81
	v_mad_i64_i32 v[82:83], s[36:37], v82, s59, v[136:137]
	v_mad_i64_i32 v[84:85], s[36:37], v81, s59, v[136:137]
	v_mov_b32_e32 v80, v249
	v_fmamk_f32 v80, v80, 0x3a800000, v155
	v_rsq_f32_e32 v80, v80
	s_nop 0
	v_pk_mul_f32 v[78:79], v[78:79], v[80:81] op_sel_hi:[1,0]
	v_pk_mul_f32 v[76:77], v[76:77], v[80:81] op_sel_hi:[1,0]
	v_pk_mul_f32 v[74:75], v[74:75], v[80:81] op_sel_hi:[1,0]
	v_pk_mul_f32 v[72:73], v[72:73], v[80:81] op_sel_hi:[1,0]
	v_pk_mul_f32 v[70:71], v[70:71], v[80:81] op_sel_hi:[1,0]
	v_pk_mul_f32 v[68:69], v[68:69], v[80:81] op_sel_hi:[1,0]
	v_pk_mul_f32 v[86:87], v[66:67], v[80:81] op_sel_hi:[1,0]
	v_pk_mul_f32 v[80:81], v[64:65], v[80:81] op_sel_hi:[1,0]
	v_cvt_pk_bf16_f32 v64, v76, v77
	v_cvt_pk_bf16_f32 v65, v78, v79
	v_cvt_pk_bf16_f32 v66, v72, v73
	v_cvt_pk_bf16_f32 v67, v74, v75
	global_store_dwordx4 v[82:83], v[64:67], off sc1
	s_nop 1
	v_cvt_pk_bf16_f32 v64, v68, v69
	v_cvt_pk_bf16_f32 v65, v70, v71
	v_cvt_pk_bf16_f32 v66, v80, v81
	v_cvt_pk_bf16_f32 v67, v86, v87
	global_store_dwordx4 v[84:85], v[64:67], off sc1
	s_nop 0
	s_nop 0
	v_add_u32_e32 v65, 0x80, v146
	v_ashrrev_i32_e32 v65, 4, v65
	v_add_u32_e32 v66, v65, v147
	v_add_u32_e32 v65, v158, v65
	v_mad_i64_i32 v[66:67], s[36:37], v66, s59, v[136:137]
	v_mad_i64_i32 v[68:69], s[36:37], v65, s59, v[136:137]
	v_mov_b32_e32 v64, v250
	v_fmamk_f32 v64, v64, 0x3a800000, v155
	v_rsq_f32_e32 v64, v64
	s_nop 0
	v_pk_mul_f32 v[62:63], v[62:63], v[64:65] op_sel_hi:[1,0]
	v_pk_mul_f32 v[60:61], v[60:61], v[64:65] op_sel_hi:[1,0]
	v_pk_mul_f32 v[58:59], v[58:59], v[64:65] op_sel_hi:[1,0]
	v_pk_mul_f32 v[56:57], v[56:57], v[64:65] op_sel_hi:[1,0]
	v_pk_mul_f32 v[54:55], v[54:55], v[64:65] op_sel_hi:[1,0]
	v_pk_mul_f32 v[52:53], v[52:53], v[64:65] op_sel_hi:[1,0]
	v_pk_mul_f32 v[70:71], v[50:51], v[64:65] op_sel_hi:[1,0]
	v_pk_mul_f32 v[64:65], v[48:49], v[64:65] op_sel_hi:[1,0]
	v_cvt_pk_bf16_f32 v48, v60, v61
	v_cvt_pk_bf16_f32 v49, v62, v63
	v_cvt_pk_bf16_f32 v50, v56, v57
	v_cvt_pk_bf16_f32 v51, v58, v59
	global_store_dwordx4 v[66:67], v[48:51], off sc1
	s_nop 1
	v_cvt_pk_bf16_f32 v48, v52, v53
	v_cvt_pk_bf16_f32 v49, v54, v55
	v_cvt_pk_bf16_f32 v50, v64, v65
	v_cvt_pk_bf16_f32 v51, v70, v71
	global_store_dwordx4 v[68:69], v[48:51], off sc1
	s_nop 0
	s_nop 0
	v_add_u32_e32 v49, 0x90, v146
	v_ashrrev_i32_e32 v49, 4, v49
	v_add_u32_e32 v50, v49, v147
	v_add_u32_e32 v49, v158, v49
	v_mad_i64_i32 v[50:51], s[36:37], v50, s59, v[136:137]
	v_mad_i64_i32 v[52:53], s[36:37], v49, s59, v[136:137]
	v_mov_b32_e32 v48, v251
	v_fmamk_f32 v48, v48, 0x3a800000, v155
	v_rsq_f32_e32 v48, v48
	s_nop 0
	v_pk_mul_f32 v[46:47], v[46:47], v[48:49] op_sel_hi:[1,0]
	v_pk_mul_f32 v[44:45], v[44:45], v[48:49] op_sel_hi:[1,0]
	v_pk_mul_f32 v[42:43], v[42:43], v[48:49] op_sel_hi:[1,0]
	v_pk_mul_f32 v[40:41], v[40:41], v[48:49] op_sel_hi:[1,0]
	v_pk_mul_f32 v[38:39], v[38:39], v[48:49] op_sel_hi:[1,0]
	v_pk_mul_f32 v[36:37], v[36:37], v[48:49] op_sel_hi:[1,0]
	v_pk_mul_f32 v[54:55], v[34:35], v[48:49] op_sel_hi:[1,0]
	v_pk_mul_f32 v[48:49], v[32:33], v[48:49] op_sel_hi:[1,0]
	v_cvt_pk_bf16_f32 v32, v44, v45
	v_cvt_pk_bf16_f32 v33, v46, v47
	v_cvt_pk_bf16_f32 v34, v40, v41
	v_cvt_pk_bf16_f32 v35, v42, v43
	global_store_dwordx4 v[50:51], v[32:35], off sc1
	s_nop 1
	v_cvt_pk_bf16_f32 v32, v36, v37
	v_cvt_pk_bf16_f32 v33, v38, v39
	v_cvt_pk_bf16_f32 v34, v48, v49
	v_cvt_pk_bf16_f32 v35, v54, v55
	global_store_dwordx4 v[52:53], v[32:35], off sc1
	s_nop 0
	s_nop 0
	v_add_u32_e32 v33, 0xa0, v146
	v_ashrrev_i32_e32 v33, 4, v33
	v_add_u32_e32 v34, v33, v147
	v_add_u32_e32 v33, v158, v33
	v_mad_i64_i32 v[34:35], s[36:37], v34, s59, v[136:137]
	v_mad_i64_i32 v[36:37], s[36:37], v33, s59, v[136:137]
	v_mov_b32_e32 v32, v252
	v_fmamk_f32 v32, v32, 0x3a800000, v155
	v_rsq_f32_e32 v32, v32
	s_nop 0
	v_pk_mul_f32 v[30:31], v[30:31], v[32:33] op_sel_hi:[1,0]
	v_pk_mul_f32 v[28:29], v[28:29], v[32:33] op_sel_hi:[1,0]
	v_pk_mul_f32 v[26:27], v[26:27], v[32:33] op_sel_hi:[1,0]
	v_pk_mul_f32 v[24:25], v[24:25], v[32:33] op_sel_hi:[1,0]
	v_pk_mul_f32 v[22:23], v[22:23], v[32:33] op_sel_hi:[1,0]
	v_pk_mul_f32 v[20:21], v[20:21], v[32:33] op_sel_hi:[1,0]
	v_pk_mul_f32 v[38:39], v[18:19], v[32:33] op_sel_hi:[1,0]
	v_pk_mul_f32 v[32:33], v[16:17], v[32:33] op_sel_hi:[1,0]
	v_cvt_pk_bf16_f32 v16, v28, v29
	v_cvt_pk_bf16_f32 v17, v30, v31
	v_cvt_pk_bf16_f32 v18, v24, v25
	v_cvt_pk_bf16_f32 v19, v26, v27
	global_store_dwordx4 v[34:35], v[16:19], off sc1
	s_nop 1
	v_cvt_pk_bf16_f32 v16, v20, v21
	v_cvt_pk_bf16_f32 v17, v22, v23
	v_cvt_pk_bf16_f32 v18, v32, v33
	v_cvt_pk_bf16_f32 v19, v38, v39
	global_store_dwordx4 v[36:37], v[16:19], off sc1
	s_nop 0
	s_nop 0
	v_add_u32_e32 v17, 0xb0, v146
	v_ashrrev_i32_e32 v17, 4, v17
	v_add_u32_e32 v18, v17, v147
	v_add_u32_e32 v17, v158, v17
	v_mad_i64_i32 v[18:19], s[4:5], v18, s59, v[136:137]
	v_mad_i64_i32 v[20:21], s[4:5], v17, s59, v[136:137]
	s_mov_b64 s[4:5], -1
	v_mov_b32_e32 v16, v253
	v_fmamk_f32 v16, v16, 0x3a800000, v155
	v_rsq_f32_e32 v16, v16
	s_nop 0
	v_pk_mul_f32 v[14:15], v[14:15], v[16:17] op_sel_hi:[1,0]
	v_pk_mul_f32 v[12:13], v[12:13], v[16:17] op_sel_hi:[1,0]
	v_pk_mul_f32 v[10:11], v[10:11], v[16:17] op_sel_hi:[1,0]
	v_pk_mul_f32 v[8:9], v[8:9], v[16:17] op_sel_hi:[1,0]
	v_pk_mul_f32 v[6:7], v[6:7], v[16:17] op_sel_hi:[1,0]
	v_pk_mul_f32 v[4:5], v[4:5], v[16:17] op_sel_hi:[1,0]
	v_pk_mul_f32 v[22:23], v[2:3], v[16:17] op_sel_hi:[1,0]
	v_pk_mul_f32 v[16:17], v[0:1], v[16:17] op_sel_hi:[1,0]
	v_cvt_pk_bf16_f32 v0, v12, v13
	v_cvt_pk_bf16_f32 v1, v14, v15
	v_cvt_pk_bf16_f32 v2, v8, v9
	v_cvt_pk_bf16_f32 v3, v10, v11
	global_store_dwordx4 v[18:19], v[0:3], off sc1
	s_nop 1
	v_cvt_pk_bf16_f32 v0, v4, v5
	v_cvt_pk_bf16_f32 v1, v6, v7
	v_cvt_pk_bf16_f32 v2, v16, v17
	v_cvt_pk_bf16_f32 v3, v22, v23
	global_store_dwordx4 v[20:21], v[0:3], off sc1
	s_cbranch_vccnz .LBB0_894
	s_andn2_b64 vcc, exec, s[8:9]
	s_cbranch_vccnz .LBB0_893
	s_barrier
	s_branch .LBB0_893

.LBB0_1123:
	s_lshl_b32 vcc_lo, s97, 8
	s_ashr_i32 s85, s84, 31
	s_and_b32 vcc_lo, vcc_lo, 0x300
	s_add_i32 vcc_lo, vcc_lo, s86
	s_lshl_b64 s[84:85], s[84:85], 10
	s_add_u32 s84, s84, vcc_lo
	s_addc_u32 s85, s85, 0
	s_mulk_i32 s85, 0x300
	s_mul_hi_u32 vcc_lo, s84, 0x300
	s_add_i32 vcc_lo, vcc_lo, s85
	s_mulk_i32 s84, 0x300
	s_add_u32 s84, s6, s84
	s_addc_u32 s85, s7, vcc_lo
	v_lshl_add_u64 v[2:3], s[84:85], 0, v[4:5]
	s_mov_b64 s[84:85], 0x6600200
	v_lshl_add_u64 v[104:105], v[2:3], 0, s[84:85]
	s_mov_b32 s84, 0x6600000
	v_cvt_pk_bf16_f32 v7, v102, v103
	v_add_co_u32_e32 v102, vcc, s84, v2
	s_mov_b64 s[84:85], 0x6600500
	s_nop 0
	v_addc_co_u32_e32 v103, vcc, 0, v3, vcc
	global_store_short v[102:103], v7, off offset:512 sc1
	global_store_short_d16_hi v[104:105], v7, off offset:128
	v_add_f32_e32 v7, v96, v101
	v_add_f32_e32 v9, v94, v79
	v_cvt_pk_bf16_f32 v7, v7, v9
	v_lshl_add_u64 v[104:105], v[2:3], 0, s[84:85]
	global_store_short v[102:103], v7, off offset:1280 sc1
	global_store_short_d16_hi v[104:105], v7, off offset:128
	v_mul_f32_e32 v7, v1, v79
	v_fma_f32 v7, v0, v101, -v7
	v_mul_f32_e32 v9, v1, v101
	v_fmac_f32_e32 v9, v0, v79
	v_add_f32_e32 v11, v98, v7
	v_add_f32_e32 v15, v99, v9
	v_cvt_pk_bf16_f32 v11, v11, v15
	v_lshl_add_u64 v[94:95], v[2:3], 0, s[14:15]
	global_store_short v[102:103], v11, off offset:2048 sc1
	global_store_short_d16_hi v[94:95], v11, off offset:128
	v_mul_f32_e32 v11, v1, v9
	v_fma_f32 v11, v0, v7, -v11
	v_mul_f32_e32 v7, v1, v7
	v_fmac_f32_e32 v7, v0, v9
	v_add_f32_e32 v9, v92, v11
	v_add_f32_e32 v15, v90, v7
	v_cvt_pk_bf16_f32 v9, v9, v15
	v_lshl_add_u64 v[94:95], v[2:3], 0, s[16:17]
	global_store_short v[102:103], v9, off offset:2816 sc1
	global_store_short_d16_hi v[94:95], v9, off offset:128
	v_mul_f32_e32 v9, v1, v7
	v_fma_f32 v9, v0, v11, -v9
	v_mul_f32_e32 v11, v1, v11
	v_fmac_f32_e32 v11, v0, v7
	v_add_f32_e32 v7, v88, v9
	v_add_f32_e32 v15, v89, v11
	v_cvt_pk_bf16_f32 v7, v7, v15
	v_lshl_add_u64 v[90:91], v[2:3], 0, s[18:19]
	global_store_short v[102:103], v7, off offset:3584 sc1
	global_store_short_d16_hi v[90:91], v7, off offset:128
	v_mul_f32_e32 v7, v1, v11
	v_fma_f32 v7, v0, v9, -v7
	v_mul_f32_e32 v9, v1, v9
	v_fmac_f32_e32 v9, v0, v11
	v_add_f32_e32 v11, v86, v7
	v_add_f32_e32 v15, v84, v9
	v_add_co_u32_e32 v84, vcc, s91, v2
	v_cvt_pk_bf16_f32 v11, v11, v15
	v_lshl_add_u64 v[88:89], v[2:3], 0, s[20:21]
	s_nop 0
	v_addc_co_u32_e32 v85, vcc, 0, v3, vcc
	global_store_short v[84:85], v11, off offset:256 sc1
	global_store_short_d16_hi v[88:89], v11, off offset:128
	v_mul_f32_e32 v11, v1, v9
	v_fma_f32 v11, v0, v7, -v11
	v_mul_f32_e32 v7, v1, v7
	v_fmac_f32_e32 v7, v0, v9
	v_add_f32_e32 v9, v82, v11
	v_add_f32_e32 v15, v83, v7
	v_cvt_pk_bf16_f32 v9, v9, v15
	v_lshl_add_u64 v[86:87], v[2:3], 0, s[22:23]
	global_store_short v[84:85], v9, off offset:1024 sc1
	global_store_short_d16_hi v[86:87], v9, off offset:128
	v_mul_f32_e32 v9, v1, v7
	v_fma_f32 v9, v0, v11, -v9
	v_mul_f32_e32 v11, v1, v11
	v_fmac_f32_e32 v11, v0, v7
	v_add_f32_e32 v7, v80, v9
	v_add_f32_e32 v15, v78, v11
	v_cvt_pk_bf16_f32 v7, v7, v15
	v_lshl_add_u64 v[82:83], v[2:3], 0, s[24:25]
	global_store_short v[84:85], v7, off offset:1792 sc1
	global_store_short_d16_hi v[82:83], v7, off offset:128
	v_mul_f32_e32 v7, v1, v11
	v_fma_f32 v7, v0, v9, -v7
	v_mul_f32_e32 v9, v1, v9
	v_fmac_f32_e32 v9, v0, v11
	v_add_f32_e32 v11, v76, v7
	v_add_f32_e32 v15, v77, v9
	v_cvt_pk_bf16_f32 v11, v11, v15
	v_lshl_add_u64 v[78:79], v[2:3], 0, s[36:37]
	global_store_short v[84:85], v11, off offset:2560 sc1
	global_store_short_d16_hi v[78:79], v11, off offset:128
	v_mul_f32_e32 v11, v1, v9
	v_fma_f32 v11, v0, v7, -v11
	v_mul_f32_e32 v7, v1, v7
	v_fmac_f32_e32 v7, v0, v9
	v_add_f32_e32 v9, v74, v11
	v_add_f32_e32 v15, v72, v7
	v_cvt_pk_bf16_f32 v9, v9, v15
	v_lshl_add_u64 v[76:77], v[2:3], 0, s[38:39]
	global_store_short v[84:85], v9, off offset:3328 sc1
	global_store_short_d16_hi v[76:77], v9, off offset:128
	v_mul_f32_e32 v9, v1, v7
	v_fma_f32 v9, v0, v11, -v9
	v_mul_f32_e32 v11, v1, v11
	v_fmac_f32_e32 v11, v0, v7
	v_add_f32_e32 v7, v70, v9
	v_add_co_u32_e32 v70, vcc, s92, v2
	v_add_f32_e32 v15, v71, v11
	v_cvt_pk_bf16_f32 v7, v7, v15
	s_nop 0
	v_addc_co_u32_e32 v71, vcc, 0, v3, vcc
	v_lshl_add_u64 v[76:77], v[2:3], 0, s[40:41]
	global_store_short v[70:71], v7, off sc1
	global_store_short_d16_hi v[76:77], v7, off offset:128
	v_mul_f32_e32 v7, v1, v11
	v_fma_f32 v7, v0, v9, -v7
	v_mul_f32_e32 v9, v1, v9
	v_fmac_f32_e32 v9, v0, v11
	v_add_f32_e32 v11, v68, v7
	v_add_f32_e32 v15, v66, v9
	v_cvt_pk_bf16_f32 v11, v11, v15
	v_lshl_add_u64 v[76:77], v[2:3], 0, s[42:43]
	global_store_short v[70:71], v11, off offset:768 sc1
	global_store_short_d16_hi v[76:77], v11, off offset:128
	v_mul_f32_e32 v11, v1, v9
	v_fma_f32 v11, v0, v7, -v11
	v_mul_f32_e32 v7, v1, v7
	v_fmac_f32_e32 v7, v0, v9
	v_add_f32_e32 v9, v64, v11
	v_add_f32_e32 v15, v65, v7
	v_cvt_pk_bf16_f32 v9, v9, v15
	v_lshl_add_u64 v[76:77], v[2:3], 0, s[44:45]
	global_store_short v[70:71], v9, off offset:1536 sc1
	global_store_short_d16_hi v[76:77], v9, off offset:128
	v_mul_f32_e32 v9, v1, v7
	v_fma_f32 v9, v0, v11, -v9
	v_mul_f32_e32 v11, v1, v11
	v_fmac_f32_e32 v11, v0, v7
	v_add_f32_e32 v7, v62, v9
	v_add_f32_e32 v15, v60, v11
	v_cvt_pk_bf16_f32 v7, v7, v15
	v_lshl_add_u64 v[64:65], v[2:3], 0, s[46:47]
	global_store_short v[70:71], v7, off offset:2304 sc1
	global_store_short_d16_hi v[64:65], v7, off offset:128
	v_mul_f32_e32 v7, v1, v11
	v_fma_f32 v7, v0, v9, -v7
	v_mul_f32_e32 v9, v1, v9
	v_fmac_f32_e32 v9, v0, v11
	v_add_f32_e32 v11, v58, v7
	v_add_f32_e32 v15, v59, v9
	v_cvt_pk_bf16_f32 v11, v11, v15
	v_lshl_add_u64 v[64:65], v[2:3], 0, s[48:49]
	global_store_short v[70:71], v11, off offset:3072 sc1
	global_store_short_d16_hi v[64:65], v11, off offset:128
	v_mul_f32_e32 v11, v1, v9
	v_fma_f32 v11, v0, v7, -v11
	v_mul_f32_e32 v7, v1, v7
	v_fmac_f32_e32 v7, v0, v9
	v_add_f32_e32 v9, v56, v11
	v_add_f32_e32 v15, v54, v7
	v_cvt_pk_bf16_f32 v9, v9, v15
	v_lshl_add_u64 v[58:59], v[2:3], 0, s[50:51]
	global_store_short v[70:71], v9, off offset:3840 sc1
	global_store_short_d16_hi v[58:59], v9, off offset:128
	v_mul_f32_e32 v9, v1, v7
	v_fma_f32 v9, v0, v11, -v9
	v_mul_f32_e32 v11, v1, v11
	v_fmac_f32_e32 v11, v0, v7
	v_add_f32_e32 v7, v52, v9
	v_add_co_u32_e32 v52, vcc, s94, v2
	v_add_f32_e32 v15, v53, v11
	v_cvt_pk_bf16_f32 v7, v7, v15
	s_nop 0
	v_addc_co_u32_e32 v53, vcc, 0, v3, vcc
	v_lshl_add_u64 v[58:59], v[2:3], 0, s[52:53]
	global_store_short v[52:53], v7, off offset:512 sc1
	global_store_short_d16_hi v[58:59], v7, off offset:128
	v_mul_f32_e32 v7, v1, v11
	v_fma_f32 v7, v0, v9, -v7
	v_mul_f32_e32 v9, v1, v9
	v_fmac_f32_e32 v9, v0, v11
	v_add_f32_e32 v11, v50, v7
	v_add_f32_e32 v15, v48, v9
	v_cvt_pk_bf16_f32 v11, v11, v15
	v_lshl_add_u64 v[58:59], v[2:3], 0, s[54:55]
	global_store_short v[52:53], v11, off offset:1280 sc1
	global_store_short_d16_hi v[58:59], v11, off offset:128
	v_mul_f32_e32 v11, v1, v9
	v_fma_f32 v11, v0, v7, -v11
	v_mul_f32_e32 v7, v1, v7
	v_fmac_f32_e32 v7, v0, v9
	v_add_f32_e32 v9, v46, v11
	v_add_f32_e32 v15, v47, v7
	v_cvt_pk_bf16_f32 v9, v9, v15
	v_lshl_add_u64 v[58:59], v[2:3], 0, s[56:57]
	global_store_short v[52:53], v9, off offset:2048 sc1
	global_store_short_d16_hi v[58:59], v9, off offset:128
	v_mul_f32_e32 v9, v1, v7
	v_fma_f32 v9, v0, v11, -v9
	v_mul_f32_e32 v11, v1, v11
	v_fmac_f32_e32 v11, v0, v7
	v_add_f32_e32 v7, v44, v9
	v_add_f32_e32 v15, v42, v11
	v_cvt_pk_bf16_f32 v7, v7, v15
	v_lshl_add_u64 v[46:47], v[2:3], 0, s[58:59]
	global_store_short v[52:53], v7, off offset:2816 sc1
	global_store_short_d16_hi v[46:47], v7, off offset:128
	v_mul_f32_e32 v7, v1, v11
	v_fma_f32 v7, v0, v9, -v7
	v_mul_f32_e32 v9, v1, v9
	v_fmac_f32_e32 v9, v0, v11
	v_add_f32_e32 v11, v40, v7
	v_add_f32_e32 v15, v41, v9
	v_cvt_pk_bf16_f32 v11, v11, v15
	v_lshl_add_u64 v[46:47], v[2:3], 0, s[60:61]
	global_store_short v[52:53], v11, off offset:3584 sc1
	global_store_short_d16_hi v[46:47], v11, off offset:128
	v_mul_f32_e32 v11, v1, v9
	v_fma_f32 v11, v0, v7, -v11
	v_mul_f32_e32 v7, v1, v7
	v_fmac_f32_e32 v7, v0, v9
	v_add_f32_e32 v9, v38, v11
	v_add_co_u32_e32 v46, vcc, s95, v2
	v_add_f32_e32 v15, v36, v7
	v_cvt_pk_bf16_f32 v9, v9, v15
	s_nop 0
	v_addc_co_u32_e32 v47, vcc, 0, v3, vcc
	v_lshl_add_u64 v[40:41], v[2:3], 0, s[62:63]
	global_store_short v[46:47], v9, off offset:256 sc1
	global_store_short_d16_hi v[40:41], v9, off offset:128
	v_mul_f32_e32 v9, v1, v7
	v_fma_f32 v9, v0, v11, -v9
	v_mul_f32_e32 v11, v1, v11
	v_fmac_f32_e32 v11, v0, v7
	v_add_f32_e32 v7, v34, v9
	v_add_f32_e32 v15, v35, v11
	v_cvt_pk_bf16_f32 v7, v7, v15
	v_lshl_add_u64 v[40:41], v[2:3], 0, s[64:65]
	global_store_short v[46:47], v7, off offset:1024 sc1
	global_store_short_d16_hi v[40:41], v7, off offset:128
	v_mul_f32_e32 v7, v1, v11
	v_fma_f32 v7, v0, v9, -v7
	v_mul_f32_e32 v9, v1, v9
	v_fmac_f32_e32 v9, v0, v11
	v_add_f32_e32 v11, v32, v7
	v_add_f32_e32 v15, v30, v9
	v_cvt_pk_bf16_f32 v11, v11, v15
	v_lshl_add_u64 v[34:35], v[2:3], 0, s[66:67]
	global_store_short v[46:47], v11, off offset:1792 sc1
	global_store_short_d16_hi v[34:35], v11, off offset:128
	v_mul_f32_e32 v11, v1, v9
	v_fma_f32 v11, v0, v7, -v11
	v_mul_f32_e32 v7, v1, v7
	v_fmac_f32_e32 v7, v0, v9
	v_add_f32_e32 v9, v28, v11
	v_add_f32_e32 v15, v29, v7
	v_cvt_pk_bf16_f32 v9, v9, v15
	v_lshl_add_u64 v[34:35], v[2:3], 0, s[68:69]
	global_store_short v[46:47], v9, off offset:2560 sc1
	global_store_short_d16_hi v[34:35], v9, off offset:128
	v_mul_f32_e32 v9, v1, v7
	v_fma_f32 v9, v0, v11, -v9
	v_mul_f32_e32 v11, v1, v11
	v_fmac_f32_e32 v11, v0, v7
	v_add_f32_e32 v7, v22, v9
	v_add_f32_e32 v15, v26, v11
	v_cvt_pk_bf16_f32 v7, v7, v15
	v_lshl_add_u64 v[28:29], v[2:3], 0, s[70:71]
	global_store_short v[46:47], v7, off offset:3328 sc1
	global_store_short_d16_hi v[28:29], v7, off offset:128
	v_mul_f32_e32 v7, v1, v11
	v_fma_f32 v7, v0, v9, -v7
	v_mul_f32_e32 v9, v1, v9
	v_fmac_f32_e32 v9, v0, v11
	v_add_f32_e32 v11, v24, v7
	v_add_co_u32_e32 v24, vcc, s96, v2
	v_add_f32_e32 v15, v25, v9
	v_cvt_pk_bf16_f32 v11, v11, v15
	s_nop 0
	v_addc_co_u32_e32 v25, vcc, 0, v3, vcc
	v_lshl_add_u64 v[28:29], v[2:3], 0, s[72:73]
	global_store_short v[24:25], v11, off sc1
	global_store_short_d16_hi v[28:29], v11, off offset:128
	v_mul_f32_e32 v11, v1, v9
	v_fma_f32 v11, v0, v7, -v11
	v_mul_f32_e32 v7, v1, v7
	v_fmac_f32_e32 v7, v0, v9
	v_add_f32_e32 v9, v16, v11
	v_add_f32_e32 v15, v20, v7
	v_cvt_pk_bf16_f32 v9, v9, v15
	v_lshl_add_u64 v[28:29], v[2:3], 0, s[74:75]
	global_store_short v[24:25], v9, off offset:768 sc1
	global_store_short_d16_hi v[28:29], v9, off offset:128
	v_mul_f32_e32 v9, v1, v7
	v_fma_f32 v9, v0, v11, -v9
	v_mul_f32_e32 v11, v1, v11
	v_fmac_f32_e32 v11, v0, v7
	v_add_f32_e32 v7, v18, v9
	v_add_f32_e32 v15, v19, v11
	v_cvt_pk_bf16_f32 v7, v7, v15
	v_lshl_add_u64 v[16:17], v[2:3], 0, s[76:77]
	global_store_short v[24:25], v7, off offset:1536 sc1
	global_store_short_d16_hi v[16:17], v7, off offset:128
	v_mul_f32_e32 v7, v1, v11
	v_fma_f32 v7, v0, v9, -v7
	v_mul_f32_e32 v9, v1, v9
	v_fmac_f32_e32 v9, v0, v11
	v_add_f32_e32 v10, v10, v7
	v_add_f32_e32 v11, v14, v9
	v_cvt_pk_bf16_f32 v10, v10, v11
	v_lshl_add_u64 v[16:17], v[2:3], 0, s[78:79]
	global_store_short v[24:25], v10, off offset:2304 sc1
	global_store_short_d16_hi v[16:17], v10, off offset:128
	v_mul_f32_e32 v10, v1, v9
	v_fma_f32 v14, v0, v7, -v10
	v_mul_f32_e32 v7, v1, v7
	v_fmac_f32_e32 v7, v0, v9
	v_add_f32_e32 v9, v12, v14
	v_add_f32_e32 v12, v13, v7
	v_cvt_pk_bf16_f32 v9, v9, v12
	v_lshl_add_u64 v[10:11], v[2:3], 0, s[80:81]
	global_store_short v[24:25], v9, off offset:3072 sc1
	global_store_short_d16_hi v[10:11], v9, off offset:128
	v_mul_f32_e32 v9, v1, v7
	v_fma_f32 v9, v0, v14, -v9
	v_mul_f32_e32 v10, v1, v14
	v_fmac_f32_e32 v10, v0, v7
	v_lshl_add_u64 v[0:1], v[2:3], 0, s[82:83]
	v_add_f32_e32 v2, v6, v9
	s_add_i32 s84, s97, 0x100
	v_add_f32_e32 v3, v8, v10
	v_cvt_pk_bf16_f32 v2, v2, v3
	s_cmp_gt_i32 s97, -1
	s_mov_b32 s97, s84
	global_store_short v[24:25], v2, off offset:3840 sc1
	global_store_short_d16_hi v[0:1], v2, off offset:128
	s_waitcnt vmcnt(63) expcnt(7) lgkmcnt(15)
	s_barrier
	s_cbranch_scc1 .LBB0_1132

.LBB0_1148:
	v_mul_f32_e32 v138, 0x3d372713, v120
	v_mul_f32_e32 v139, 0x3d372713, v124
	v_fma_f32 v138, v120, v138, 1.0
	v_fma_f32 v139, v124, v139, 1.0
	v_mul_f32_e32 v147, 0x3d372713, v121
	v_mul_f32_e32 v138, v120, v138
	v_mul_f32_e32 v139, v124, v139
	v_fma_f32 v147, v121, v147, 1.0
	v_mul_f32_e32 v138, 0x3fcc422a, v138
	v_mul_f32_e32 v139, 0x3fcc422a, v139
	v_mul_f32_e32 v147, v121, v147
	v_mul_f32_e32 v138, 0xbfb8aa3b, v138
	v_mul_f32_e32 v139, 0xbfb8aa3b, v139
	v_mul_f32_e32 v147, 0x3fcc422a, v147
	v_exp_f32_e32 v138, v138
	v_exp_f32_e32 v139, v139
	v_mul_f32_e32 v147, 0xbfb8aa3b, v147
	v_exp_f32_e32 v147, v147
	v_add_f32_e32 v138, 1.0, v138
	v_add_f32_e32 v139, 1.0, v139
	v_mul_f32_e32 v148, 0x3d372713, v125
	v_rcp_f32_e32 v138, v138
	v_rcp_f32_e32 v139, v139
	v_add_f32_e32 v147, 1.0, v147
	v_fma_f32 v148, v125, v148, 1.0
	v_rcp_f32_e32 v147, v147
	v_mul_f32_e32 v148, v125, v148
	v_mul_f32_e32 v148, 0x3fcc422a, v148
	v_mul_f32_e32 v148, 0xbfb8aa3b, v148
	v_exp_f32_e32 v148, v148
	v_mul_f32_e32 v120, v120, v138
	v_mul_f32_e32 v138, v124, v139
	v_mul_f32_e32 v139, 0x3d372713, v122
	v_mul_f32_e32 v121, v121, v147
	v_fma_f32 v139, v122, v139, 1.0
	v_mul_f32_e32 v147, 0x3d372713, v126
	v_mul_f32_e32 v139, v122, v139
	v_fma_f32 v147, v126, v147, 1.0
	v_mul_f32_e32 v139, 0x3fcc422a, v139
	v_mul_f32_e32 v147, v126, v147
	v_add_f32_e32 v124, 1.0, v148
	v_mul_f32_e32 v139, 0xbfb8aa3b, v139
	v_mul_f32_e32 v147, 0x3fcc422a, v147
	v_rcp_f32_e32 v124, v124
	v_exp_f32_e32 v139, v139
	v_mul_f32_e32 v147, 0xbfb8aa3b, v147
	v_exp_f32_e32 v147, v147
	v_mul_f32_e32 v148, v125, v124
	v_add_f32_e32 v124, 1.0, v139
	v_mul_f32_e32 v139, 0x3d372713, v123
	v_add_f32_e32 v125, 1.0, v147
	v_fma_f32 v139, v123, v139, 1.0
	v_mul_f32_e32 v147, 0x3d372713, v127
	v_mul_f32_e32 v139, v123, v139
	v_fma_f32 v147, v127, v147, 1.0
	v_mul_f32_e32 v139, 0x3fcc422a, v139
	v_mul_f32_e32 v147, v127, v147
	v_mul_f32_e32 v139, 0xbfb8aa3b, v139
	v_mul_f32_e32 v147, 0x3fcc422a, v147
	v_exp_f32_e32 v139, v139
	v_mul_f32_e32 v147, 0xbfb8aa3b, v147
	v_rcp_f32_e32 v124, v124
	v_exp_f32_e32 v147, v147
	v_mov_b32_e32 v142, v209
	v_mov_b32_e32 v137, v254
	v_add_f32_e32 v139, 1.0, v139
	v_lshlrev_b32_e32 v146, 4, v137
	v_and_b32_e32 v143, 0x3ff0, v146
	v_rcp_f32_e32 v125, v125
	v_rcp_f32_e32 v139, v139
	v_add_f32_e32 v147, 1.0, v147
	v_mul_f32_e32 v149, v122, v124
	v_ashrrev_i32_e32 v122, 4, v142
	s_lshl_b32 s43, s65, 4
	v_rcp_f32_e32 v147, v147
	v_cvt_pk_bf16_f32 v124, v120, v121
	v_add_u32_e32 v120, v143, v122
	v_and_or_b32 v136, v142, 15, s43
	v_ashrrev_i32_e32 v121, 31, v120
	v_ashrrev_i32_e32 v137, 31, v136
	v_lshlrev_b64 v[120:121], 11, v[120:121]
	v_mul_f32_e32 v150, v126, v125
	v_mul_f32_e32 v123, v123, v139
	v_cvt_pk_bf16_f32 v125, v149, v123
	v_cvt_pk_bf16_f32 v126, v138, v148
	v_lshl_add_u64 v[138:139], s[14:15], 0, v[120:121]
	v_lshlrev_b64 v[120:121], 1, v[136:137]
	v_mul_f32_e32 v127, v127, v147
	v_lshl_add_u64 v[136:137], v[138:139], 0, v[120:121]
	v_cvt_pk_bf16_f32 v127, v150, v127
	global_store_dwordx4 v[136:137], v[124:127], off sc1
	v_mul_f32_e32 v123, 0x3d372713, v112
	v_fma_f32 v123, v112, v123, 1.0
	v_mul_f32_e32 v125, 0x3d372713, v116
	v_mul_f32_e32 v126, 0x3d372713, v113
	v_fma_f32 v125, v116, v125, 1.0
	v_fma_f32 v126, v113, v126, 1.0
	v_mul_f32_e32 v125, v116, v125
	v_mul_f32_e32 v126, v113, v126
	v_mul_f32_e32 v125, 0x3fcc422a, v125
	v_mul_f32_e32 v126, 0x3fcc422a, v126
	v_mul_f32_e32 v125, 0xbfb8aa3b, v125
	v_mul_f32_e32 v126, 0xbfb8aa3b, v126
	v_exp_f32_e32 v125, v125
	v_exp_f32_e32 v126, v126
	v_mul_f32_e32 v123, v112, v123
	v_mul_f32_e32 v123, 0x3fcc422a, v123
	v_mul_f32_e32 v123, 0xbfb8aa3b, v123
	v_exp_f32_e32 v123, v123
	v_add_f32_e32 v125, 1.0, v125
	v_add_f32_e32 v126, 1.0, v126
	v_mul_f32_e32 v127, 0x3d372713, v117
	v_rcp_f32_e32 v125, v125
	v_rcp_f32_e32 v126, v126
	v_fma_f32 v127, v117, v127, 1.0
	v_mul_f32_e32 v127, v117, v127
	v_mul_f32_e32 v127, 0x3fcc422a, v127
	v_add_f32_e32 v123, 1.0, v123
	v_mul_f32_e32 v127, 0xbfb8aa3b, v127
	v_rcp_f32_e32 v123, v123
	v_exp_f32_e32 v127, v127
	v_mul_f32_e32 v116, v116, v125
	v_mul_f32_e32 v113, v113, v126
	v_mul_f32_e32 v125, 0x3d372713, v114
	v_mul_f32_e32 v126, 0x3d372713, v118
	v_fma_f32 v125, v114, v125, 1.0
	v_fma_f32 v126, v118, v126, 1.0
	v_mul_f32_e32 v125, v114, v125
	v_mul_f32_e32 v126, v118, v126
	v_mul_f32_e32 v125, 0x3fcc422a, v125
	v_mul_f32_e32 v126, 0x3fcc422a, v126
	v_mul_f32_e32 v123, v112, v123
	v_add_f32_e32 v112, 1.0, v127
	v_mul_f32_e32 v125, 0xbfb8aa3b, v125
	v_mul_f32_e32 v126, 0xbfb8aa3b, v126
	v_rcp_f32_e32 v112, v112
	v_exp_f32_e32 v125, v125
	v_exp_f32_e32 v126, v126
	v_mul_f32_e32 v127, 0x3d372713, v119
	v_mul_f32_e32 v117, v117, v112
	v_add_f32_e32 v112, 1.0, v125
	v_add_f32_e32 v125, 1.0, v126
	v_mul_f32_e32 v126, 0x3d372713, v115
	v_fma_f32 v126, v115, v126, 1.0
	v_mul_f32_e32 v126, v115, v126
	v_fma_f32 v127, v119, v127, 1.0
	v_mul_f32_e32 v126, 0x3fcc422a, v126
	v_mul_f32_e32 v127, v119, v127
	v_mul_f32_e32 v126, 0xbfb8aa3b, v126
	v_mul_f32_e32 v127, 0x3fcc422a, v127
	v_exp_f32_e32 v126, v126
	v_mul_f32_e32 v127, 0xbfb8aa3b, v127
	v_exp_f32_e32 v127, v127
	v_rcp_f32_e32 v112, v112
	v_add_f32_e32 v126, 1.0, v126
	v_rcp_f32_e32 v125, v125
	v_rcp_f32_e32 v126, v126
	v_add_f32_e32 v127, 1.0, v127
	v_rcp_f32_e32 v127, v127
	v_add_u32_e32 v124, 0x80, v142
	v_mul_f32_e32 v136, v114, v112
	v_mul_f32_e32 v118, v118, v125
	v_mul_f32_e32 v115, v115, v126
	v_ashrrev_i32_e32 v112, 4, v124
	v_mul_f32_e32 v119, v119, v127
	v_cvt_pk_bf16_f32 v114, v123, v113
	v_cvt_pk_bf16_f32 v115, v136, v115
	v_cvt_pk_bf16_f32 v116, v116, v117
	v_cvt_pk_bf16_f32 v117, v118, v119
	v_add_u32_e32 v118, v112, v143
	v_ashrrev_i32_e32 v119, 31, v118
	v_lshlrev_b64 v[118:119], 11, v[118:119]
	v_lshl_add_u64 v[118:119], s[14:15], 0, v[118:119]
	v_lshl_add_u64 v[118:119], v[118:119], 0, v[120:121]
	global_store_dwordx4 v[118:119], v[114:117], off sc1
	v_mul_f32_e32 v113, 0x3d372713, v104
	v_fma_f32 v113, v104, v113, 1.0
	v_mul_f32_e32 v115, 0x3d372713, v108
	v_mul_f32_e32 v116, 0x3d372713, v105
	v_fma_f32 v115, v108, v115, 1.0
	v_fma_f32 v116, v105, v116, 1.0
	v_mul_f32_e32 v115, v108, v115
	v_mul_f32_e32 v116, v105, v116
	v_mul_f32_e32 v115, 0x3fcc422a, v115
	v_mul_f32_e32 v116, 0x3fcc422a, v116
	v_mul_f32_e32 v115, 0xbfb8aa3b, v115
	v_mul_f32_e32 v116, 0xbfb8aa3b, v116
	v_exp_f32_e32 v115, v115
	v_exp_f32_e32 v116, v116
	v_mul_f32_e32 v113, v104, v113
	v_mul_f32_e32 v113, 0x3fcc422a, v113
	v_mul_f32_e32 v113, 0xbfb8aa3b, v113
	v_exp_f32_e32 v113, v113
	v_add_f32_e32 v115, 1.0, v115
	v_add_f32_e32 v116, 1.0, v116
	v_mul_f32_e32 v117, 0x3d372713, v109
	v_rcp_f32_e32 v115, v115
	v_rcp_f32_e32 v116, v116
	v_fma_f32 v117, v109, v117, 1.0
	v_mul_f32_e32 v117, v109, v117
	v_mul_f32_e32 v117, 0x3fcc422a, v117
	v_add_f32_e32 v113, 1.0, v113
	v_mul_f32_e32 v117, 0xbfb8aa3b, v117
	v_rcp_f32_e32 v113, v113
	v_exp_f32_e32 v117, v117
	v_mul_f32_e32 v108, v108, v115
	v_mul_f32_e32 v105, v105, v116
	v_mul_f32_e32 v115, 0x3d372713, v106
	v_mul_f32_e32 v116, 0x3d372713, v110
	v_fma_f32 v115, v106, v115, 1.0
	v_fma_f32 v116, v110, v116, 1.0
	v_mul_f32_e32 v115, v106, v115
	v_mul_f32_e32 v116, v110, v116
	v_mul_f32_e32 v115, 0x3fcc422a, v115
	v_mul_f32_e32 v116, 0x3fcc422a, v116
	v_mul_f32_e32 v104, v104, v113
	v_add_f32_e32 v113, 1.0, v117
	v_mul_f32_e32 v115, 0xbfb8aa3b, v115
	v_mul_f32_e32 v116, 0xbfb8aa3b, v116
	v_rcp_f32_e32 v113, v113
	v_exp_f32_e32 v115, v115
	v_exp_f32_e32 v116, v116
	v_mul_f32_e32 v117, 0x3d372713, v111
	v_mul_f32_e32 v109, v109, v113
	v_add_f32_e32 v113, 1.0, v115
	v_add_f32_e32 v115, 1.0, v116
	v_mul_f32_e32 v116, 0x3d372713, v107
	v_fma_f32 v116, v107, v116, 1.0
	v_mul_f32_e32 v116, v107, v116
	v_mul_f32_e32 v116, 0x3fcc422a, v116
	v_mul_f32_e32 v116, 0xbfb8aa3b, v116
	v_exp_f32_e32 v116, v116
	v_fma_f32 v117, v111, v117, 1.0
	v_mul_f32_e32 v117, v111, v117
	v_mul_f32_e32 v117, 0x3fcc422a, v117
	v_rcp_f32_e32 v113, v113
	v_mul_f32_e32 v117, 0xbfb8aa3b, v117
	v_add_f32_e32 v116, 1.0, v116
	v_exp_f32_e32 v117, v117
	v_rcp_f32_e32 v116, v116
	v_add_u32_e32 v114, 0x100, v146
	v_and_b32_e32 v114, 0x3ff0, v114
	v_mul_f32_e32 v106, v106, v113
	v_add_f32_e32 v117, 1.0, v117
	v_mul_f32_e32 v107, v107, v116
	v_cvt_pk_bf16_f32 v104, v104, v105
	v_cvt_pk_bf16_f32 v105, v106, v107
	v_cvt_pk_bf16_f32 v106, v108, v109
	v_add_u32_e32 v108, v114, v122
	v_rcp_f32_e32 v115, v115
	v_rcp_f32_e32 v117, v117
	v_ashrrev_i32_e32 v109, 31, v108
	v_lshlrev_b64 v[108:109], 11, v[108:109]
	v_lshl_add_u64 v[108:109], s[14:15], 0, v[108:109]
	v_lshl_add_u64 v[108:109], v[108:109], 0, v[120:121]
	v_mul_f32_e32 v110, v110, v115
	v_mul_f32_e32 v111, v111, v117
	v_cvt_pk_bf16_f32 v107, v110, v111
	global_store_dwordx4 v[108:109], v[104:107], off sc1
	v_mul_f32_e32 v110, 0x3d372713, v96
	v_fma_f32 v110, v96, v110, 1.0
	v_mul_f32_e32 v105, 0x3d372713, v100
	v_mul_f32_e32 v106, 0x3d372713, v97
	v_fma_f32 v105, v100, v105, 1.0
	v_fma_f32 v106, v97, v106, 1.0
	v_mul_f32_e32 v105, v100, v105
	v_mul_f32_e32 v106, v97, v106
	v_mul_f32_e32 v105, 0x3fcc422a, v105
	v_mul_f32_e32 v106, 0x3fcc422a, v106
	v_mul_f32_e32 v105, 0xbfb8aa3b, v105
	v_mul_f32_e32 v106, 0xbfb8aa3b, v106
	v_exp_f32_e32 v105, v105
	v_exp_f32_e32 v106, v106
	v_mul_f32_e32 v110, v96, v110
	v_mul_f32_e32 v110, 0x3fcc422a, v110
	v_mul_f32_e32 v110, 0xbfb8aa3b, v110
	v_exp_f32_e32 v110, v110
	v_add_f32_e32 v105, 1.0, v105
	v_add_f32_e32 v106, 1.0, v106
	v_mul_f32_e32 v107, 0x3d372713, v101
	v_rcp_f32_e32 v105, v105
	v_rcp_f32_e32 v106, v106
	v_fma_f32 v107, v101, v107, 1.0
	v_mul_f32_e32 v107, v101, v107
	v_mul_f32_e32 v107, 0x3fcc422a, v107
	v_add_f32_e32 v104, 1.0, v110
	v_mul_f32_e32 v107, 0xbfb8aa3b, v107
	v_rcp_f32_e32 v104, v104
	v_exp_f32_e32 v107, v107
	v_mul_f32_e32 v100, v100, v105
	v_mul_f32_e32 v97, v97, v106
	v_mul_f32_e32 v105, 0x3d372713, v98
	v_mul_f32_e32 v106, 0x3d372713, v102
	v_fma_f32 v105, v98, v105, 1.0
	v_fma_f32 v106, v102, v106, 1.0
	v_mul_f32_e32 v105, v98, v105
	v_mul_f32_e32 v106, v102, v106
	v_mul_f32_e32 v105, 0x3fcc422a, v105
	v_mul_f32_e32 v106, 0x3fcc422a, v106
	v_mul_f32_e32 v96, v96, v104
	v_add_f32_e32 v104, 1.0, v107
	v_mul_f32_e32 v105, 0xbfb8aa3b, v105
	v_mul_f32_e32 v106, 0xbfb8aa3b, v106
	v_rcp_f32_e32 v104, v104
	v_exp_f32_e32 v105, v105
	v_exp_f32_e32 v106, v106
	v_mul_f32_e32 v107, 0x3d372713, v103
	v_mul_f32_e32 v101, v101, v104
	v_add_f32_e32 v104, 1.0, v105
	v_add_f32_e32 v105, 1.0, v106
	v_mul_f32_e32 v106, 0x3d372713, v99
	v_fma_f32 v106, v99, v106, 1.0
	v_mul_f32_e32 v106, v99, v106
	v_mul_f32_e32 v106, 0x3fcc422a, v106
	v_mul_f32_e32 v106, 0xbfb8aa3b, v106
	v_exp_f32_e32 v106, v106
	v_fma_f32 v107, v103, v107, 1.0
	v_mul_f32_e32 v107, v103, v107
	v_mul_f32_e32 v107, 0x3fcc422a, v107
	v_mul_f32_e32 v107, 0xbfb8aa3b, v107
	v_rcp_f32_e32 v104, v104
	v_exp_f32_e32 v107, v107
	v_add_f32_e32 v106, 1.0, v106
	v_rcp_f32_e32 v106, v106
	v_mul_f32_e32 v98, v98, v104
	v_add_f32_e32 v107, 1.0, v107
	v_rcp_f32_e32 v105, v105
	v_rcp_f32_e32 v107, v107
	v_mul_f32_e32 v99, v99, v106
	v_cvt_pk_bf16_f32 v96, v96, v97
	v_cvt_pk_bf16_f32 v97, v98, v99
	v_cvt_pk_bf16_f32 v98, v100, v101
	v_add_u32_e32 v100, v114, v112
	v_ashrrev_i32_e32 v101, 31, v100
	v_lshlrev_b64 v[100:101], 11, v[100:101]
	v_lshl_add_u64 v[100:101], s[14:15], 0, v[100:101]
	v_mul_f32_e32 v102, v102, v105
	v_mul_f32_e32 v103, v103, v107
	v_cvt_pk_bf16_f32 v99, v102, v103
	v_lshl_add_u64 v[100:101], v[100:101], 0, v[120:121]
	global_store_dwordx4 v[100:101], v[96:99], off sc1
	v_mul_f32_e32 v102, 0x3d372713, v88
	v_fma_f32 v102, v88, v102, 1.0
	v_mul_f32_e32 v98, 0x3d372713, v92
	v_mul_f32_e32 v99, 0x3d372713, v89
	v_fma_f32 v98, v92, v98, 1.0
	v_fma_f32 v99, v89, v99, 1.0
	v_mul_f32_e32 v98, v92, v98
	v_mul_f32_e32 v99, v89, v99
	v_mul_f32_e32 v98, 0x3fcc422a, v98
	v_mul_f32_e32 v99, 0x3fcc422a, v99
	v_mul_f32_e32 v98, 0xbfb8aa3b, v98
	v_mul_f32_e32 v99, 0xbfb8aa3b, v99
	v_exp_f32_e32 v98, v98
	v_exp_f32_e32 v99, v99
	v_mul_f32_e32 v102, v88, v102
	v_mul_f32_e32 v102, 0x3fcc422a, v102
	v_mul_f32_e32 v102, 0xbfb8aa3b, v102
	v_exp_f32_e32 v102, v102
	v_add_f32_e32 v98, 1.0, v98
	v_add_f32_e32 v99, 1.0, v99
	v_mul_f32_e32 v100, 0x3d372713, v93
	v_rcp_f32_e32 v98, v98
	v_rcp_f32_e32 v99, v99
	v_fma_f32 v100, v93, v100, 1.0
	v_mul_f32_e32 v100, v93, v100
	v_mul_f32_e32 v100, 0x3fcc422a, v100
	v_add_f32_e32 v97, 1.0, v102
	v_mul_f32_e32 v100, 0xbfb8aa3b, v100
	v_rcp_f32_e32 v97, v97
	v_exp_f32_e32 v100, v100
	v_mul_f32_e32 v92, v92, v98
	v_mul_f32_e32 v89, v89, v99
	v_mul_f32_e32 v98, 0x3d372713, v90
	v_mul_f32_e32 v99, 0x3d372713, v94
	v_fma_f32 v98, v90, v98, 1.0
	v_fma_f32 v99, v94, v99, 1.0
	v_mul_f32_e32 v98, v90, v98
	v_mul_f32_e32 v99, v94, v99
	v_mul_f32_e32 v98, 0x3fcc422a, v98
	v_mul_f32_e32 v99, 0x3fcc422a, v99
	v_mul_f32_e32 v88, v88, v97
	v_add_f32_e32 v97, 1.0, v100
	v_mul_f32_e32 v98, 0xbfb8aa3b, v98
	v_mul_f32_e32 v99, 0xbfb8aa3b, v99
	v_rcp_f32_e32 v97, v97
	v_exp_f32_e32 v98, v98
	v_exp_f32_e32 v99, v99
	v_mul_f32_e32 v100, 0x3d372713, v95
	v_mul_f32_e32 v93, v93, v97
	v_add_f32_e32 v97, 1.0, v98
	v_add_f32_e32 v98, 1.0, v99
	v_mul_f32_e32 v99, 0x3d372713, v91
	v_fma_f32 v99, v91, v99, 1.0
	v_mul_f32_e32 v99, v91, v99
	v_mul_f32_e32 v99, 0x3fcc422a, v99
	v_mul_f32_e32 v99, 0xbfb8aa3b, v99
	v_exp_f32_e32 v99, v99
	v_fma_f32 v100, v95, v100, 1.0
	v_mul_f32_e32 v100, v95, v100
	v_mul_f32_e32 v100, 0x3fcc422a, v100
	v_rcp_f32_e32 v97, v97
	v_mul_f32_e32 v100, 0xbfb8aa3b, v100
	v_add_f32_e32 v99, 1.0, v99
	v_exp_f32_e32 v100, v100
	v_rcp_f32_e32 v99, v99
	v_add_u32_e32 v96, 0x200, v146
	v_and_b32_e32 v96, 0x3ff0, v96
	v_mul_f32_e32 v90, v90, v97
	v_add_f32_e32 v100, 1.0, v100
	v_mul_f32_e32 v91, v91, v99
	v_cvt_pk_bf16_f32 v88, v88, v89
	v_cvt_pk_bf16_f32 v89, v90, v91
	v_cvt_pk_bf16_f32 v90, v92, v93
	v_add_u32_e32 v92, v96, v122
	v_rcp_f32_e32 v98, v98
	v_rcp_f32_e32 v100, v100
	v_ashrrev_i32_e32 v93, 31, v92
	v_lshlrev_b64 v[92:93], 11, v[92:93]
	v_lshl_add_u64 v[92:93], s[14:15], 0, v[92:93]
	v_lshl_add_u64 v[92:93], v[92:93], 0, v[120:121]
	v_mul_f32_e32 v94, v94, v98
	v_mul_f32_e32 v95, v95, v100
	v_cvt_pk_bf16_f32 v91, v94, v95
	global_store_dwordx4 v[92:93], v[88:91], off sc1
	v_mul_f32_e32 v94, 0x3d372713, v80
	v_fma_f32 v94, v80, v94, 1.0
	v_mul_f32_e32 v89, 0x3d372713, v84
	v_mul_f32_e32 v90, 0x3d372713, v81
	v_fma_f32 v89, v84, v89, 1.0
	v_fma_f32 v90, v81, v90, 1.0
	v_mul_f32_e32 v89, v84, v89
	v_mul_f32_e32 v90, v81, v90
	v_mul_f32_e32 v89, 0x3fcc422a, v89
	v_mul_f32_e32 v90, 0x3fcc422a, v90
	v_mul_f32_e32 v89, 0xbfb8aa3b, v89
	v_mul_f32_e32 v90, 0xbfb8aa3b, v90
	v_exp_f32_e32 v89, v89
	v_exp_f32_e32 v90, v90
	v_mul_f32_e32 v94, v80, v94
	v_mul_f32_e32 v94, 0x3fcc422a, v94
	v_mul_f32_e32 v94, 0xbfb8aa3b, v94
	v_exp_f32_e32 v94, v94
	v_add_f32_e32 v89, 1.0, v89
	v_add_f32_e32 v90, 1.0, v90
	v_mul_f32_e32 v91, 0x3d372713, v85
	v_rcp_f32_e32 v89, v89
	v_rcp_f32_e32 v90, v90
	v_fma_f32 v91, v85, v91, 1.0
	v_mul_f32_e32 v91, v85, v91
	v_mul_f32_e32 v91, 0x3fcc422a, v91
	v_add_f32_e32 v88, 1.0, v94
	v_mul_f32_e32 v91, 0xbfb8aa3b, v91
	v_rcp_f32_e32 v88, v88
	v_exp_f32_e32 v91, v91
	v_mul_f32_e32 v84, v84, v89
	v_mul_f32_e32 v81, v81, v90
	v_mul_f32_e32 v89, 0x3d372713, v82
	v_mul_f32_e32 v90, 0x3d372713, v86
	v_fma_f32 v89, v82, v89, 1.0
	v_fma_f32 v90, v86, v90, 1.0
	v_mul_f32_e32 v89, v82, v89
	v_mul_f32_e32 v90, v86, v90
	v_mul_f32_e32 v89, 0x3fcc422a, v89
	v_mul_f32_e32 v90, 0x3fcc422a, v90
	v_mul_f32_e32 v80, v80, v88
	v_add_f32_e32 v88, 1.0, v91
	v_mul_f32_e32 v89, 0xbfb8aa3b, v89
	v_mul_f32_e32 v90, 0xbfb8aa3b, v90
	v_rcp_f32_e32 v88, v88
	v_exp_f32_e32 v89, v89
	v_exp_f32_e32 v90, v90
	v_mul_f32_e32 v91, 0x3d372713, v87
	v_mul_f32_e32 v85, v85, v88
	v_add_f32_e32 v88, 1.0, v89
	v_add_f32_e32 v89, 1.0, v90
	v_mul_f32_e32 v90, 0x3d372713, v83
	v_fma_f32 v90, v83, v90, 1.0
	v_mul_f32_e32 v90, v83, v90
	v_mul_f32_e32 v90, 0x3fcc422a, v90
	v_mul_f32_e32 v90, 0xbfb8aa3b, v90
	v_exp_f32_e32 v90, v90
	v_fma_f32 v91, v87, v91, 1.0
	v_mul_f32_e32 v91, v87, v91
	v_mul_f32_e32 v91, 0x3fcc422a, v91
	v_mul_f32_e32 v91, 0xbfb8aa3b, v91
	v_rcp_f32_e32 v88, v88
	v_exp_f32_e32 v91, v91
	v_add_f32_e32 v90, 1.0, v90
	v_rcp_f32_e32 v90, v90
	v_mul_f32_e32 v82, v82, v88
	v_add_f32_e32 v91, 1.0, v91
	v_rcp_f32_e32 v89, v89
	v_rcp_f32_e32 v91, v91
	v_mul_f32_e32 v83, v83, v90
	v_cvt_pk_bf16_f32 v80, v80, v81
	v_cvt_pk_bf16_f32 v81, v82, v83
	v_cvt_pk_bf16_f32 v82, v84, v85
	v_add_u32_e32 v84, v96, v112
	v_ashrrev_i32_e32 v85, 31, v84
	v_lshlrev_b64 v[84:85], 11, v[84:85]
	v_lshl_add_u64 v[84:85], s[14:15], 0, v[84:85]
	v_mul_f32_e32 v86, v86, v89
	v_mul_f32_e32 v87, v87, v91
	v_cvt_pk_bf16_f32 v83, v86, v87
	v_lshl_add_u64 v[84:85], v[84:85], 0, v[120:121]
	global_store_dwordx4 v[84:85], v[80:83], off sc1
	v_mul_f32_e32 v86, 0x3d372713, v72
	v_fma_f32 v86, v72, v86, 1.0
	v_mul_f32_e32 v82, 0x3d372713, v76
	v_mul_f32_e32 v83, 0x3d372713, v73
	v_fma_f32 v82, v76, v82, 1.0
	v_fma_f32 v83, v73, v83, 1.0
	v_mul_f32_e32 v82, v76, v82
	v_mul_f32_e32 v83, v73, v83
	v_mul_f32_e32 v82, 0x3fcc422a, v82
	v_mul_f32_e32 v83, 0x3fcc422a, v83
	v_mul_f32_e32 v82, 0xbfb8aa3b, v82
	v_mul_f32_e32 v83, 0xbfb8aa3b, v83
	v_exp_f32_e32 v82, v82
	v_exp_f32_e32 v83, v83
	v_mul_f32_e32 v86, v72, v86
	v_mul_f32_e32 v86, 0x3fcc422a, v86
	v_mul_f32_e32 v86, 0xbfb8aa3b, v86
	v_exp_f32_e32 v86, v86
	v_add_f32_e32 v82, 1.0, v82
	v_add_f32_e32 v83, 1.0, v83
	v_mul_f32_e32 v84, 0x3d372713, v77
	v_rcp_f32_e32 v82, v82
	v_rcp_f32_e32 v83, v83
	v_fma_f32 v84, v77, v84, 1.0
	v_mul_f32_e32 v84, v77, v84
	v_mul_f32_e32 v84, 0x3fcc422a, v84
	v_add_f32_e32 v81, 1.0, v86
	v_mul_f32_e32 v84, 0xbfb8aa3b, v84
	v_rcp_f32_e32 v81, v81
	v_exp_f32_e32 v84, v84
	v_mul_f32_e32 v76, v76, v82
	v_mul_f32_e32 v73, v73, v83
	v_mul_f32_e32 v82, 0x3d372713, v74
	v_mul_f32_e32 v83, 0x3d372713, v78
	v_fma_f32 v82, v74, v82, 1.0
	v_fma_f32 v83, v78, v83, 1.0
	v_mul_f32_e32 v82, v74, v82
	v_mul_f32_e32 v83, v78, v83
	v_mul_f32_e32 v82, 0x3fcc422a, v82
	v_mul_f32_e32 v83, 0x3fcc422a, v83
	v_mul_f32_e32 v72, v72, v81
	v_add_f32_e32 v81, 1.0, v84
	v_mul_f32_e32 v82, 0xbfb8aa3b, v82
	v_mul_f32_e32 v83, 0xbfb8aa3b, v83
	v_rcp_f32_e32 v81, v81
	v_exp_f32_e32 v82, v82
	v_exp_f32_e32 v83, v83
	v_mul_f32_e32 v84, 0x3d372713, v79
	v_mul_f32_e32 v77, v77, v81
	v_add_f32_e32 v81, 1.0, v82
	v_add_f32_e32 v82, 1.0, v83
	v_mul_f32_e32 v83, 0x3d372713, v75
	v_fma_f32 v83, v75, v83, 1.0
	v_mul_f32_e32 v83, v75, v83
	v_mul_f32_e32 v83, 0x3fcc422a, v83
	v_mul_f32_e32 v83, 0xbfb8aa3b, v83
	v_exp_f32_e32 v83, v83
	v_fma_f32 v84, v79, v84, 1.0
	v_mul_f32_e32 v84, v79, v84
	v_mul_f32_e32 v84, 0x3fcc422a, v84
	v_rcp_f32_e32 v81, v81
	v_mul_f32_e32 v84, 0xbfb8aa3b, v84
	v_add_f32_e32 v83, 1.0, v83
	v_exp_f32_e32 v84, v84
	v_rcp_f32_e32 v83, v83
	v_add_u32_e32 v80, 0x300, v146
	v_and_b32_e32 v80, 0x3ff0, v80
	v_mul_f32_e32 v74, v74, v81
	v_add_f32_e32 v84, 1.0, v84
	v_mul_f32_e32 v75, v75, v83
	v_cvt_pk_bf16_f32 v72, v72, v73
	v_cvt_pk_bf16_f32 v73, v74, v75
	v_cvt_pk_bf16_f32 v74, v76, v77
	v_add_u32_e32 v76, v80, v122
	v_rcp_f32_e32 v82, v82
	v_rcp_f32_e32 v84, v84
	v_ashrrev_i32_e32 v77, 31, v76
	v_lshlrev_b64 v[76:77], 11, v[76:77]
	v_lshl_add_u64 v[76:77], s[14:15], 0, v[76:77]
	v_lshl_add_u64 v[76:77], v[76:77], 0, v[120:121]
	v_mul_f32_e32 v78, v78, v82
	v_mul_f32_e32 v79, v79, v84
	v_cvt_pk_bf16_f32 v75, v78, v79
	global_store_dwordx4 v[76:77], v[72:75], off sc1
	v_mul_f32_e32 v78, 0x3d372713, v64
	v_fma_f32 v78, v64, v78, 1.0
	v_mul_f32_e32 v73, 0x3d372713, v68
	v_mul_f32_e32 v74, 0x3d372713, v65
	v_fma_f32 v73, v68, v73, 1.0
	v_fma_f32 v74, v65, v74, 1.0
	v_mul_f32_e32 v73, v68, v73
	v_mul_f32_e32 v74, v65, v74
	v_mul_f32_e32 v73, 0x3fcc422a, v73
	v_mul_f32_e32 v74, 0x3fcc422a, v74
	v_mul_f32_e32 v73, 0xbfb8aa3b, v73
	v_mul_f32_e32 v74, 0xbfb8aa3b, v74
	v_exp_f32_e32 v73, v73
	v_exp_f32_e32 v74, v74
	v_mul_f32_e32 v78, v64, v78
	v_mul_f32_e32 v78, 0x3fcc422a, v78
	v_mul_f32_e32 v78, 0xbfb8aa3b, v78
	v_exp_f32_e32 v78, v78
	v_add_f32_e32 v73, 1.0, v73
	v_add_f32_e32 v74, 1.0, v74
	v_mul_f32_e32 v75, 0x3d372713, v69
	v_rcp_f32_e32 v73, v73
	v_rcp_f32_e32 v74, v74
	v_fma_f32 v75, v69, v75, 1.0
	v_mul_f32_e32 v75, v69, v75
	v_mul_f32_e32 v75, 0x3fcc422a, v75
	v_add_f32_e32 v72, 1.0, v78
	v_mul_f32_e32 v75, 0xbfb8aa3b, v75
	v_rcp_f32_e32 v72, v72
	v_exp_f32_e32 v75, v75
	v_mul_f32_e32 v68, v68, v73
	v_mul_f32_e32 v65, v65, v74
	v_mul_f32_e32 v73, 0x3d372713, v66
	v_mul_f32_e32 v74, 0x3d372713, v70
	v_fma_f32 v73, v66, v73, 1.0
	v_fma_f32 v74, v70, v74, 1.0
	v_mul_f32_e32 v73, v66, v73
	v_mul_f32_e32 v74, v70, v74
	v_mul_f32_e32 v73, 0x3fcc422a, v73
	v_mul_f32_e32 v74, 0x3fcc422a, v74
	v_mul_f32_e32 v64, v64, v72
	v_add_f32_e32 v72, 1.0, v75
	v_mul_f32_e32 v73, 0xbfb8aa3b, v73
	v_mul_f32_e32 v74, 0xbfb8aa3b, v74
	v_rcp_f32_e32 v72, v72
	v_exp_f32_e32 v73, v73
	v_exp_f32_e32 v74, v74
	v_mul_f32_e32 v75, 0x3d372713, v71
	v_mul_f32_e32 v69, v69, v72
	v_add_f32_e32 v72, 1.0, v73
	v_add_f32_e32 v73, 1.0, v74
	v_mul_f32_e32 v74, 0x3d372713, v67
	v_fma_f32 v74, v67, v74, 1.0
	v_mul_f32_e32 v74, v67, v74
	v_mul_f32_e32 v74, 0x3fcc422a, v74
	v_mul_f32_e32 v74, 0xbfb8aa3b, v74
	v_exp_f32_e32 v74, v74
	v_fma_f32 v75, v71, v75, 1.0
	v_mul_f32_e32 v75, v71, v75
	v_mul_f32_e32 v75, 0x3fcc422a, v75
	v_mul_f32_e32 v75, 0xbfb8aa3b, v75
	v_rcp_f32_e32 v72, v72
	v_exp_f32_e32 v75, v75
	v_add_f32_e32 v74, 1.0, v74
	v_rcp_f32_e32 v74, v74
	v_mul_f32_e32 v66, v66, v72
	v_add_f32_e32 v75, 1.0, v75
	v_rcp_f32_e32 v73, v73
	v_rcp_f32_e32 v75, v75
	v_mul_f32_e32 v67, v67, v74
	v_cvt_pk_bf16_f32 v64, v64, v65
	v_cvt_pk_bf16_f32 v65, v66, v67
	v_cvt_pk_bf16_f32 v66, v68, v69
	v_add_u32_e32 v68, v80, v112
	v_ashrrev_i32_e32 v69, 31, v68
	v_lshlrev_b64 v[68:69], 11, v[68:69]
	v_lshl_add_u64 v[68:69], s[14:15], 0, v[68:69]
	v_mul_f32_e32 v70, v70, v73
	v_mul_f32_e32 v71, v71, v75
	v_cvt_pk_bf16_f32 v67, v70, v71
	v_lshl_add_u64 v[68:69], v[68:69], 0, v[120:121]
	global_store_dwordx4 v[68:69], v[64:67], off sc1
	v_mul_f32_e32 v70, 0x3d372713, v56
	v_fma_f32 v70, v56, v70, 1.0
	v_mul_f32_e32 v66, 0x3d372713, v60
	v_mul_f32_e32 v67, 0x3d372713, v57
	v_fma_f32 v66, v60, v66, 1.0
	v_fma_f32 v67, v57, v67, 1.0
	v_mul_f32_e32 v66, v60, v66
	v_mul_f32_e32 v67, v57, v67
	v_mul_f32_e32 v66, 0x3fcc422a, v66
	v_mul_f32_e32 v67, 0x3fcc422a, v67
	v_mul_f32_e32 v66, 0xbfb8aa3b, v66
	v_mul_f32_e32 v67, 0xbfb8aa3b, v67
	v_exp_f32_e32 v66, v66
	v_exp_f32_e32 v67, v67
	v_mul_f32_e32 v70, v56, v70
	v_mul_f32_e32 v70, 0x3fcc422a, v70
	v_mul_f32_e32 v70, 0xbfb8aa3b, v70
	v_exp_f32_e32 v70, v70
	v_add_f32_e32 v66, 1.0, v66
	v_add_f32_e32 v67, 1.0, v67
	v_mul_f32_e32 v68, 0x3d372713, v61
	v_rcp_f32_e32 v66, v66
	v_rcp_f32_e32 v67, v67
	v_fma_f32 v68, v61, v68, 1.0
	v_mul_f32_e32 v68, v61, v68
	v_mul_f32_e32 v68, 0x3fcc422a, v68
	v_add_f32_e32 v65, 1.0, v70
	v_mul_f32_e32 v68, 0xbfb8aa3b, v68
	v_rcp_f32_e32 v65, v65
	v_exp_f32_e32 v68, v68
	v_mul_f32_e32 v60, v60, v66
	v_mul_f32_e32 v57, v57, v67
	v_mul_f32_e32 v66, 0x3d372713, v58
	v_mul_f32_e32 v67, 0x3d372713, v62
	v_fma_f32 v66, v58, v66, 1.0
	v_fma_f32 v67, v62, v67, 1.0
	v_mul_f32_e32 v66, v58, v66
	v_mul_f32_e32 v67, v62, v67
	v_mul_f32_e32 v66, 0x3fcc422a, v66
	v_mul_f32_e32 v67, 0x3fcc422a, v67
	v_mul_f32_e32 v56, v56, v65
	v_add_f32_e32 v65, 1.0, v68
	v_mul_f32_e32 v66, 0xbfb8aa3b, v66
	v_mul_f32_e32 v67, 0xbfb8aa3b, v67
	v_rcp_f32_e32 v65, v65
	v_exp_f32_e32 v66, v66
	v_exp_f32_e32 v67, v67
	v_mul_f32_e32 v68, 0x3d372713, v63
	v_mul_f32_e32 v61, v61, v65
	v_add_f32_e32 v65, 1.0, v66
	v_add_f32_e32 v66, 1.0, v67
	v_mul_f32_e32 v67, 0x3d372713, v59
	v_fma_f32 v67, v59, v67, 1.0
	v_mul_f32_e32 v67, v59, v67
	v_mul_f32_e32 v67, 0x3fcc422a, v67
	v_mul_f32_e32 v67, 0xbfb8aa3b, v67
	v_exp_f32_e32 v67, v67
	v_fma_f32 v68, v63, v68, 1.0
	v_mul_f32_e32 v68, v63, v68
	v_mul_f32_e32 v68, 0x3fcc422a, v68
	v_rcp_f32_e32 v65, v65
	v_mul_f32_e32 v68, 0xbfb8aa3b, v68
	v_add_f32_e32 v67, 1.0, v67
	v_exp_f32_e32 v68, v68
	v_rcp_f32_e32 v67, v67
	v_add_u32_e32 v64, 0x800, v146
	v_and_b32_e32 v64, 0x3ff0, v64
	v_mul_f32_e32 v58, v58, v65
	v_add_f32_e32 v68, 1.0, v68
	v_mul_f32_e32 v59, v59, v67
	v_cvt_pk_bf16_f32 v56, v56, v57
	v_cvt_pk_bf16_f32 v57, v58, v59
	v_cvt_pk_bf16_f32 v58, v60, v61
	v_add_u32_e32 v60, v64, v122
	v_rcp_f32_e32 v66, v66
	v_rcp_f32_e32 v68, v68
	v_ashrrev_i32_e32 v61, 31, v60
	v_lshlrev_b64 v[60:61], 11, v[60:61]
	v_lshl_add_u64 v[60:61], s[14:15], 0, v[60:61]
	v_lshl_add_u64 v[60:61], v[60:61], 0, v[120:121]
	v_mul_f32_e32 v62, v62, v66
	v_mul_f32_e32 v63, v63, v68
	v_cvt_pk_bf16_f32 v59, v62, v63
	global_store_dwordx4 v[60:61], v[56:59], off sc1
	v_mul_f32_e32 v62, 0x3d372713, v48
	v_fma_f32 v62, v48, v62, 1.0
	v_mul_f32_e32 v57, 0x3d372713, v52
	v_mul_f32_e32 v58, 0x3d372713, v49
	v_fma_f32 v57, v52, v57, 1.0
	v_fma_f32 v58, v49, v58, 1.0
	v_mul_f32_e32 v57, v52, v57
	v_mul_f32_e32 v58, v49, v58
	v_mul_f32_e32 v57, 0x3fcc422a, v57
	v_mul_f32_e32 v58, 0x3fcc422a, v58
	v_mul_f32_e32 v57, 0xbfb8aa3b, v57
	v_mul_f32_e32 v58, 0xbfb8aa3b, v58
	v_exp_f32_e32 v57, v57
	v_exp_f32_e32 v58, v58
	v_mul_f32_e32 v62, v48, v62
	v_mul_f32_e32 v62, 0x3fcc422a, v62
	v_mul_f32_e32 v62, 0xbfb8aa3b, v62
	v_exp_f32_e32 v62, v62
	v_add_f32_e32 v57, 1.0, v57
	v_add_f32_e32 v58, 1.0, v58
	v_mul_f32_e32 v59, 0x3d372713, v53
	v_rcp_f32_e32 v57, v57
	v_rcp_f32_e32 v58, v58
	v_fma_f32 v59, v53, v59, 1.0
	v_mul_f32_e32 v59, v53, v59
	v_mul_f32_e32 v59, 0x3fcc422a, v59
	v_add_f32_e32 v56, 1.0, v62
	v_mul_f32_e32 v59, 0xbfb8aa3b, v59
	v_rcp_f32_e32 v56, v56
	v_exp_f32_e32 v59, v59
	v_mul_f32_e32 v52, v52, v57
	v_mul_f32_e32 v49, v49, v58
	v_mul_f32_e32 v57, 0x3d372713, v50
	v_mul_f32_e32 v58, 0x3d372713, v54
	v_fma_f32 v57, v50, v57, 1.0
	v_fma_f32 v58, v54, v58, 1.0
	v_mul_f32_e32 v57, v50, v57
	v_mul_f32_e32 v58, v54, v58
	v_mul_f32_e32 v57, 0x3fcc422a, v57
	v_mul_f32_e32 v58, 0x3fcc422a, v58
	v_mul_f32_e32 v48, v48, v56
	v_add_f32_e32 v56, 1.0, v59
	v_mul_f32_e32 v57, 0xbfb8aa3b, v57
	v_mul_f32_e32 v58, 0xbfb8aa3b, v58
	v_rcp_f32_e32 v56, v56
	v_exp_f32_e32 v57, v57
	v_exp_f32_e32 v58, v58
	v_mul_f32_e32 v59, 0x3d372713, v55
	v_mul_f32_e32 v53, v53, v56
	v_add_f32_e32 v56, 1.0, v57
	v_add_f32_e32 v57, 1.0, v58
	v_mul_f32_e32 v58, 0x3d372713, v51
	v_fma_f32 v58, v51, v58, 1.0
	v_mul_f32_e32 v58, v51, v58
	v_mul_f32_e32 v58, 0x3fcc422a, v58
	v_mul_f32_e32 v58, 0xbfb8aa3b, v58
	v_exp_f32_e32 v58, v58
	v_fma_f32 v59, v55, v59, 1.0
	v_mul_f32_e32 v59, v55, v59
	v_mul_f32_e32 v59, 0x3fcc422a, v59
	v_mul_f32_e32 v59, 0xbfb8aa3b, v59
	v_rcp_f32_e32 v56, v56
	v_exp_f32_e32 v59, v59
	v_add_f32_e32 v58, 1.0, v58
	v_rcp_f32_e32 v58, v58
	v_mul_f32_e32 v50, v50, v56
	v_add_f32_e32 v59, 1.0, v59
	v_rcp_f32_e32 v57, v57
	v_rcp_f32_e32 v59, v59
	v_mul_f32_e32 v51, v51, v58
	v_cvt_pk_bf16_f32 v48, v48, v49
	v_cvt_pk_bf16_f32 v49, v50, v51
	v_cvt_pk_bf16_f32 v50, v52, v53
	v_add_u32_e32 v52, v64, v112
	v_ashrrev_i32_e32 v53, 31, v52
	v_lshlrev_b64 v[52:53], 11, v[52:53]
	v_lshl_add_u64 v[52:53], s[14:15], 0, v[52:53]
	v_mul_f32_e32 v54, v54, v57
	v_mul_f32_e32 v55, v55, v59
	v_cvt_pk_bf16_f32 v51, v54, v55
	v_lshl_add_u64 v[52:53], v[52:53], 0, v[120:121]
	global_store_dwordx4 v[52:53], v[48:51], off sc1
	v_mul_f32_e32 v54, 0x3d372713, v40
	v_fma_f32 v54, v40, v54, 1.0
	v_mul_f32_e32 v50, 0x3d372713, v44
	v_mul_f32_e32 v51, 0x3d372713, v41
	v_fma_f32 v50, v44, v50, 1.0
	v_fma_f32 v51, v41, v51, 1.0
	v_mul_f32_e32 v50, v44, v50
	v_mul_f32_e32 v51, v41, v51
	v_mul_f32_e32 v50, 0x3fcc422a, v50
	v_mul_f32_e32 v51, 0x3fcc422a, v51
	v_mul_f32_e32 v50, 0xbfb8aa3b, v50
	v_mul_f32_e32 v51, 0xbfb8aa3b, v51
	v_exp_f32_e32 v50, v50
	v_exp_f32_e32 v51, v51
	v_mul_f32_e32 v54, v40, v54
	v_mul_f32_e32 v54, 0x3fcc422a, v54
	v_mul_f32_e32 v54, 0xbfb8aa3b, v54
	v_exp_f32_e32 v54, v54
	v_add_f32_e32 v50, 1.0, v50
	v_add_f32_e32 v51, 1.0, v51
	v_mul_f32_e32 v52, 0x3d372713, v45
	v_rcp_f32_e32 v50, v50
	v_rcp_f32_e32 v51, v51
	v_fma_f32 v52, v45, v52, 1.0
	v_mul_f32_e32 v52, v45, v52
	v_mul_f32_e32 v52, 0x3fcc422a, v52
	v_add_f32_e32 v49, 1.0, v54
	v_mul_f32_e32 v52, 0xbfb8aa3b, v52
	v_rcp_f32_e32 v49, v49
	v_exp_f32_e32 v52, v52
	v_mul_f32_e32 v44, v44, v50
	v_mul_f32_e32 v41, v41, v51
	v_mul_f32_e32 v50, 0x3d372713, v42
	v_mul_f32_e32 v51, 0x3d372713, v46
	v_fma_f32 v50, v42, v50, 1.0
	v_fma_f32 v51, v46, v51, 1.0
	v_mul_f32_e32 v50, v42, v50
	v_mul_f32_e32 v51, v46, v51
	v_mul_f32_e32 v50, 0x3fcc422a, v50
	v_mul_f32_e32 v51, 0x3fcc422a, v51
	v_mul_f32_e32 v40, v40, v49
	v_add_f32_e32 v49, 1.0, v52
	v_mul_f32_e32 v50, 0xbfb8aa3b, v50
	v_mul_f32_e32 v51, 0xbfb8aa3b, v51
	v_rcp_f32_e32 v49, v49
	v_exp_f32_e32 v50, v50
	v_exp_f32_e32 v51, v51
	v_mul_f32_e32 v52, 0x3d372713, v47
	v_mul_f32_e32 v45, v45, v49
	v_add_f32_e32 v49, 1.0, v50
	v_add_f32_e32 v50, 1.0, v51
	v_mul_f32_e32 v51, 0x3d372713, v43
	v_fma_f32 v51, v43, v51, 1.0
	v_mul_f32_e32 v51, v43, v51
	v_mul_f32_e32 v51, 0x3fcc422a, v51
	v_mul_f32_e32 v51, 0xbfb8aa3b, v51
	v_exp_f32_e32 v51, v51
	v_fma_f32 v52, v47, v52, 1.0
	v_mul_f32_e32 v52, v47, v52
	v_mul_f32_e32 v52, 0x3fcc422a, v52
	v_rcp_f32_e32 v49, v49
	v_mul_f32_e32 v52, 0xbfb8aa3b, v52
	v_add_f32_e32 v51, 1.0, v51
	v_exp_f32_e32 v52, v52
	v_rcp_f32_e32 v51, v51
	v_add_u32_e32 v48, 0x900, v146
	v_and_b32_e32 v48, 0x3ff0, v48
	v_mul_f32_e32 v42, v42, v49
	v_add_f32_e32 v52, 1.0, v52
	v_mul_f32_e32 v43, v43, v51
	v_cvt_pk_bf16_f32 v40, v40, v41
	v_cvt_pk_bf16_f32 v41, v42, v43
	v_cvt_pk_bf16_f32 v42, v44, v45
	v_add_u32_e32 v44, v48, v122
	v_rcp_f32_e32 v50, v50
	v_rcp_f32_e32 v52, v52
	v_ashrrev_i32_e32 v45, 31, v44
	v_lshlrev_b64 v[44:45], 11, v[44:45]
	v_lshl_add_u64 v[44:45], s[14:15], 0, v[44:45]
	v_lshl_add_u64 v[44:45], v[44:45], 0, v[120:121]
	v_mul_f32_e32 v46, v46, v50
	v_mul_f32_e32 v47, v47, v52
	v_cvt_pk_bf16_f32 v43, v46, v47
	global_store_dwordx4 v[44:45], v[40:43], off sc1
	v_mul_f32_e32 v46, 0x3d372713, v32
	v_fma_f32 v46, v32, v46, 1.0
	v_mul_f32_e32 v41, 0x3d372713, v36
	v_mul_f32_e32 v42, 0x3d372713, v33
	v_fma_f32 v41, v36, v41, 1.0
	v_fma_f32 v42, v33, v42, 1.0
	v_mul_f32_e32 v41, v36, v41
	v_mul_f32_e32 v42, v33, v42
	v_mul_f32_e32 v41, 0x3fcc422a, v41
	v_mul_f32_e32 v42, 0x3fcc422a, v42
	v_mul_f32_e32 v41, 0xbfb8aa3b, v41
	v_mul_f32_e32 v42, 0xbfb8aa3b, v42
	v_exp_f32_e32 v41, v41
	v_exp_f32_e32 v42, v42
	v_mul_f32_e32 v46, v32, v46
	v_mul_f32_e32 v46, 0x3fcc422a, v46
	v_mul_f32_e32 v46, 0xbfb8aa3b, v46
	v_exp_f32_e32 v46, v46
	v_add_f32_e32 v41, 1.0, v41
	v_add_f32_e32 v42, 1.0, v42
	v_mul_f32_e32 v43, 0x3d372713, v37
	v_rcp_f32_e32 v41, v41
	v_rcp_f32_e32 v42, v42
	v_fma_f32 v43, v37, v43, 1.0
	v_mul_f32_e32 v43, v37, v43
	v_mul_f32_e32 v43, 0x3fcc422a, v43
	v_add_f32_e32 v40, 1.0, v46
	v_mul_f32_e32 v43, 0xbfb8aa3b, v43
	v_rcp_f32_e32 v40, v40
	v_exp_f32_e32 v43, v43
	v_mul_f32_e32 v36, v36, v41
	v_mul_f32_e32 v33, v33, v42
	v_mul_f32_e32 v41, 0x3d372713, v34
	v_mul_f32_e32 v42, 0x3d372713, v38
	v_fma_f32 v41, v34, v41, 1.0
	v_fma_f32 v42, v38, v42, 1.0
	v_mul_f32_e32 v41, v34, v41
	v_mul_f32_e32 v42, v38, v42
	v_mul_f32_e32 v41, 0x3fcc422a, v41
	v_mul_f32_e32 v42, 0x3fcc422a, v42
	v_mul_f32_e32 v32, v32, v40
	v_add_f32_e32 v40, 1.0, v43
	v_mul_f32_e32 v41, 0xbfb8aa3b, v41
	v_mul_f32_e32 v42, 0xbfb8aa3b, v42
	v_rcp_f32_e32 v40, v40
	v_exp_f32_e32 v41, v41
	v_exp_f32_e32 v42, v42
	v_mul_f32_e32 v43, 0x3d372713, v39
	v_mul_f32_e32 v37, v37, v40
	v_add_f32_e32 v40, 1.0, v41
	v_add_f32_e32 v41, 1.0, v42
	v_mul_f32_e32 v42, 0x3d372713, v35
	v_fma_f32 v42, v35, v42, 1.0
	v_mul_f32_e32 v42, v35, v42
	v_mul_f32_e32 v42, 0x3fcc422a, v42
	v_mul_f32_e32 v42, 0xbfb8aa3b, v42
	v_exp_f32_e32 v42, v42
	v_fma_f32 v43, v39, v43, 1.0
	v_mul_f32_e32 v43, v39, v43
	v_mul_f32_e32 v43, 0x3fcc422a, v43
	v_mul_f32_e32 v43, 0xbfb8aa3b, v43
	v_rcp_f32_e32 v40, v40
	v_exp_f32_e32 v43, v43
	v_add_f32_e32 v42, 1.0, v42
	v_rcp_f32_e32 v42, v42
	v_mul_f32_e32 v34, v34, v40
	v_add_f32_e32 v43, 1.0, v43
	v_rcp_f32_e32 v41, v41
	v_rcp_f32_e32 v43, v43
	v_mul_f32_e32 v35, v35, v42
	v_cvt_pk_bf16_f32 v32, v32, v33
	v_cvt_pk_bf16_f32 v33, v34, v35
	v_cvt_pk_bf16_f32 v34, v36, v37
	v_add_u32_e32 v36, v48, v112
	v_ashrrev_i32_e32 v37, 31, v36
	v_lshlrev_b64 v[36:37], 11, v[36:37]
	v_lshl_add_u64 v[36:37], s[14:15], 0, v[36:37]
	v_mul_f32_e32 v38, v38, v41
	v_mul_f32_e32 v39, v39, v43
	v_cvt_pk_bf16_f32 v35, v38, v39
	v_lshl_add_u64 v[36:37], v[36:37], 0, v[120:121]
	global_store_dwordx4 v[36:37], v[32:35], off sc1
	v_mul_f32_e32 v38, 0x3d372713, v24
	v_fma_f32 v38, v24, v38, 1.0
	v_mul_f32_e32 v34, 0x3d372713, v28
	v_mul_f32_e32 v35, 0x3d372713, v25
	v_fma_f32 v34, v28, v34, 1.0
	v_fma_f32 v35, v25, v35, 1.0
	v_mul_f32_e32 v34, v28, v34
	v_mul_f32_e32 v35, v25, v35
	v_mul_f32_e32 v34, 0x3fcc422a, v34
	v_mul_f32_e32 v35, 0x3fcc422a, v35
	v_mul_f32_e32 v34, 0xbfb8aa3b, v34
	v_mul_f32_e32 v35, 0xbfb8aa3b, v35
	v_exp_f32_e32 v34, v34
	v_exp_f32_e32 v35, v35
	v_mul_f32_e32 v38, v24, v38
	v_mul_f32_e32 v38, 0x3fcc422a, v38
	v_mul_f32_e32 v38, 0xbfb8aa3b, v38
	v_exp_f32_e32 v38, v38
	v_add_f32_e32 v34, 1.0, v34
	v_add_f32_e32 v35, 1.0, v35
	v_mul_f32_e32 v36, 0x3d372713, v29
	v_rcp_f32_e32 v34, v34
	v_rcp_f32_e32 v35, v35
	v_fma_f32 v36, v29, v36, 1.0
	v_mul_f32_e32 v36, v29, v36
	v_mul_f32_e32 v36, 0x3fcc422a, v36
	v_add_f32_e32 v33, 1.0, v38
	v_mul_f32_e32 v36, 0xbfb8aa3b, v36
	v_rcp_f32_e32 v33, v33
	v_exp_f32_e32 v36, v36
	v_mul_f32_e32 v28, v28, v34
	v_mul_f32_e32 v25, v25, v35
	v_mul_f32_e32 v34, 0x3d372713, v26
	v_mul_f32_e32 v35, 0x3d372713, v30
	v_fma_f32 v34, v26, v34, 1.0
	v_fma_f32 v35, v30, v35, 1.0
	v_mul_f32_e32 v34, v26, v34
	v_mul_f32_e32 v35, v30, v35
	v_mul_f32_e32 v34, 0x3fcc422a, v34
	v_mul_f32_e32 v35, 0x3fcc422a, v35
	v_mul_f32_e32 v24, v24, v33
	v_add_f32_e32 v33, 1.0, v36
	v_mul_f32_e32 v34, 0xbfb8aa3b, v34
	v_mul_f32_e32 v35, 0xbfb8aa3b, v35
	v_rcp_f32_e32 v33, v33
	v_exp_f32_e32 v34, v34
	v_exp_f32_e32 v35, v35
	v_mul_f32_e32 v36, 0x3d372713, v31
	v_mul_f32_e32 v29, v29, v33
	v_add_f32_e32 v33, 1.0, v34
	v_add_f32_e32 v34, 1.0, v35
	v_mul_f32_e32 v35, 0x3d372713, v27
	v_fma_f32 v35, v27, v35, 1.0
	v_mul_f32_e32 v35, v27, v35
	v_mul_f32_e32 v35, 0x3fcc422a, v35
	v_mul_f32_e32 v35, 0xbfb8aa3b, v35
	v_exp_f32_e32 v35, v35
	v_fma_f32 v36, v31, v36, 1.0
	v_mul_f32_e32 v36, v31, v36
	v_mul_f32_e32 v36, 0x3fcc422a, v36
	v_rcp_f32_e32 v33, v33
	v_mul_f32_e32 v36, 0xbfb8aa3b, v36
	v_add_f32_e32 v35, 1.0, v35
	v_exp_f32_e32 v36, v36
	v_rcp_f32_e32 v35, v35
	v_add_u32_e32 v32, 0xa00, v146
	v_and_b32_e32 v32, 0x3ff0, v32
	v_mul_f32_e32 v26, v26, v33
	v_add_f32_e32 v36, 1.0, v36
	v_mul_f32_e32 v27, v27, v35
	v_cvt_pk_bf16_f32 v24, v24, v25
	v_cvt_pk_bf16_f32 v25, v26, v27
	v_cvt_pk_bf16_f32 v26, v28, v29
	v_add_u32_e32 v28, v32, v122
	v_rcp_f32_e32 v34, v34
	v_rcp_f32_e32 v36, v36
	v_ashrrev_i32_e32 v29, 31, v28
	v_lshlrev_b64 v[28:29], 11, v[28:29]
	v_lshl_add_u64 v[28:29], s[14:15], 0, v[28:29]
	v_lshl_add_u64 v[28:29], v[28:29], 0, v[120:121]
	v_mul_f32_e32 v30, v30, v34
	v_mul_f32_e32 v31, v31, v36
	v_cvt_pk_bf16_f32 v27, v30, v31
	global_store_dwordx4 v[28:29], v[24:27], off sc1
	v_mul_f32_e32 v30, 0x3d372713, v16
	v_fma_f32 v30, v16, v30, 1.0
	v_mul_f32_e32 v25, 0x3d372713, v20
	v_mul_f32_e32 v26, 0x3d372713, v17
	v_fma_f32 v25, v20, v25, 1.0
	v_fma_f32 v26, v17, v26, 1.0
	v_mul_f32_e32 v25, v20, v25
	v_mul_f32_e32 v26, v17, v26
	v_mul_f32_e32 v25, 0x3fcc422a, v25
	v_mul_f32_e32 v26, 0x3fcc422a, v26
	v_mul_f32_e32 v25, 0xbfb8aa3b, v25
	v_mul_f32_e32 v26, 0xbfb8aa3b, v26
	v_exp_f32_e32 v25, v25
	v_exp_f32_e32 v26, v26
	v_mul_f32_e32 v30, v16, v30
	v_mul_f32_e32 v30, 0x3fcc422a, v30
	v_mul_f32_e32 v30, 0xbfb8aa3b, v30
	v_exp_f32_e32 v30, v30
	v_add_f32_e32 v25, 1.0, v25
	v_add_f32_e32 v26, 1.0, v26
	v_mul_f32_e32 v27, 0x3d372713, v21
	v_rcp_f32_e32 v25, v25
	v_rcp_f32_e32 v26, v26
	v_fma_f32 v27, v21, v27, 1.0
	v_mul_f32_e32 v27, v21, v27
	v_mul_f32_e32 v27, 0x3fcc422a, v27
	v_add_f32_e32 v24, 1.0, v30
	v_mul_f32_e32 v27, 0xbfb8aa3b, v27
	v_rcp_f32_e32 v24, v24
	v_exp_f32_e32 v27, v27
	v_mul_f32_e32 v20, v20, v25
	v_mul_f32_e32 v17, v17, v26
	v_mul_f32_e32 v25, 0x3d372713, v18
	v_mul_f32_e32 v26, 0x3d372713, v22
	v_fma_f32 v25, v18, v25, 1.0
	v_fma_f32 v26, v22, v26, 1.0
	v_mul_f32_e32 v25, v18, v25
	v_mul_f32_e32 v26, v22, v26
	v_mul_f32_e32 v25, 0x3fcc422a, v25
	v_mul_f32_e32 v26, 0x3fcc422a, v26
	v_mul_f32_e32 v16, v16, v24
	v_add_f32_e32 v24, 1.0, v27
	v_mul_f32_e32 v25, 0xbfb8aa3b, v25
	v_mul_f32_e32 v26, 0xbfb8aa3b, v26
	v_rcp_f32_e32 v24, v24
	v_exp_f32_e32 v25, v25
	v_exp_f32_e32 v26, v26
	v_mul_f32_e32 v27, 0x3d372713, v23
	v_mul_f32_e32 v21, v21, v24
	v_add_f32_e32 v24, 1.0, v25
	v_add_f32_e32 v25, 1.0, v26
	v_mul_f32_e32 v26, 0x3d372713, v19
	v_fma_f32 v26, v19, v26, 1.0
	v_mul_f32_e32 v26, v19, v26
	v_mul_f32_e32 v26, 0x3fcc422a, v26
	v_mul_f32_e32 v26, 0xbfb8aa3b, v26
	v_exp_f32_e32 v26, v26
	v_fma_f32 v27, v23, v27, 1.0
	v_mul_f32_e32 v27, v23, v27
	v_mul_f32_e32 v27, 0x3fcc422a, v27
	v_mul_f32_e32 v27, 0xbfb8aa3b, v27
	v_rcp_f32_e32 v24, v24
	v_exp_f32_e32 v27, v27
	v_add_f32_e32 v26, 1.0, v26
	v_rcp_f32_e32 v26, v26
	v_mul_f32_e32 v18, v18, v24
	v_add_f32_e32 v27, 1.0, v27
	v_rcp_f32_e32 v25, v25
	v_rcp_f32_e32 v27, v27
	v_mul_f32_e32 v19, v19, v26
	v_cvt_pk_bf16_f32 v16, v16, v17
	v_cvt_pk_bf16_f32 v17, v18, v19
	v_cvt_pk_bf16_f32 v18, v20, v21
	v_add_u32_e32 v20, v32, v112
	v_ashrrev_i32_e32 v21, 31, v20
	v_lshlrev_b64 v[20:21], 11, v[20:21]
	v_lshl_add_u64 v[20:21], s[14:15], 0, v[20:21]
	v_mul_f32_e32 v22, v22, v25
	v_mul_f32_e32 v23, v23, v27
	v_cvt_pk_bf16_f32 v19, v22, v23
	v_lshl_add_u64 v[20:21], v[20:21], 0, v[120:121]
	global_store_dwordx4 v[20:21], v[16:19], off sc1
	v_mul_f32_e32 v22, 0x3d372713, v8
	v_fma_f32 v22, v8, v22, 1.0
	v_mul_f32_e32 v18, 0x3d372713, v12
	v_mul_f32_e32 v19, 0x3d372713, v9
	v_fma_f32 v18, v12, v18, 1.0
	v_fma_f32 v19, v9, v19, 1.0
	v_mul_f32_e32 v18, v12, v18
	v_mul_f32_e32 v19, v9, v19
	v_mul_f32_e32 v18, 0x3fcc422a, v18
	v_mul_f32_e32 v19, 0x3fcc422a, v19
	v_mul_f32_e32 v18, 0xbfb8aa3b, v18
	v_mul_f32_e32 v19, 0xbfb8aa3b, v19
	v_exp_f32_e32 v18, v18
	v_exp_f32_e32 v19, v19
	v_mul_f32_e32 v22, v8, v22
	v_mul_f32_e32 v22, 0x3fcc422a, v22
	v_mul_f32_e32 v22, 0xbfb8aa3b, v22
	v_exp_f32_e32 v22, v22
	v_add_f32_e32 v18, 1.0, v18
	v_add_f32_e32 v19, 1.0, v19
	v_mul_f32_e32 v20, 0x3d372713, v13
	v_rcp_f32_e32 v18, v18
	v_rcp_f32_e32 v19, v19
	v_fma_f32 v20, v13, v20, 1.0
	v_mul_f32_e32 v20, v13, v20
	v_mul_f32_e32 v20, 0x3fcc422a, v20
	v_add_f32_e32 v17, 1.0, v22
	v_mul_f32_e32 v20, 0xbfb8aa3b, v20
	v_rcp_f32_e32 v17, v17
	v_exp_f32_e32 v20, v20
	v_mul_f32_e32 v12, v12, v18
	v_mul_f32_e32 v9, v9, v19
	v_mul_f32_e32 v18, 0x3d372713, v10
	v_mul_f32_e32 v19, 0x3d372713, v14
	v_fma_f32 v18, v10, v18, 1.0
	v_fma_f32 v19, v14, v19, 1.0
	v_mul_f32_e32 v18, v10, v18
	v_mul_f32_e32 v19, v14, v19
	v_mul_f32_e32 v18, 0x3fcc422a, v18
	v_mul_f32_e32 v19, 0x3fcc422a, v19
	v_mul_f32_e32 v8, v8, v17
	v_add_f32_e32 v17, 1.0, v20
	v_mul_f32_e32 v18, 0xbfb8aa3b, v18
	v_mul_f32_e32 v19, 0xbfb8aa3b, v19
	v_rcp_f32_e32 v17, v17
	v_exp_f32_e32 v18, v18
	v_exp_f32_e32 v19, v19
	v_mul_f32_e32 v20, 0x3d372713, v15
	v_mul_f32_e32 v13, v13, v17
	v_add_f32_e32 v17, 1.0, v18
	v_add_f32_e32 v18, 1.0, v19
	v_mul_f32_e32 v19, 0x3d372713, v11
	v_fma_f32 v19, v11, v19, 1.0
	v_mul_f32_e32 v19, v11, v19
	v_mul_f32_e32 v19, 0x3fcc422a, v19
	v_mul_f32_e32 v19, 0xbfb8aa3b, v19
	v_exp_f32_e32 v19, v19
	v_fma_f32 v20, v15, v20, 1.0
	v_mul_f32_e32 v20, v15, v20
	v_mul_f32_e32 v20, 0x3fcc422a, v20
	v_rcp_f32_e32 v17, v17
	v_mul_f32_e32 v20, 0xbfb8aa3b, v20
	v_add_f32_e32 v19, 1.0, v19
	v_exp_f32_e32 v20, v20
	v_rcp_f32_e32 v19, v19
	v_add_u32_e32 v16, 0xb00, v146
	v_and_b32_e32 v16, 0x3ff0, v16
	v_mul_f32_e32 v10, v10, v17
	v_add_f32_e32 v20, 1.0, v20
	v_mul_f32_e32 v11, v11, v19
	v_cvt_pk_bf16_f32 v8, v8, v9
	v_cvt_pk_bf16_f32 v9, v10, v11
	v_cvt_pk_bf16_f32 v10, v12, v13
	v_add_u32_e32 v12, v16, v122
	v_rcp_f32_e32 v18, v18
	v_rcp_f32_e32 v20, v20
	v_ashrrev_i32_e32 v13, 31, v12
	v_lshlrev_b64 v[12:13], 11, v[12:13]
	v_lshl_add_u64 v[12:13], s[14:15], 0, v[12:13]
	v_lshl_add_u64 v[12:13], v[12:13], 0, v[120:121]
	v_mul_f32_e32 v14, v14, v18
	v_mul_f32_e32 v15, v15, v20
	v_cvt_pk_bf16_f32 v11, v14, v15
	global_store_dwordx4 v[12:13], v[8:11], off sc1
	v_mul_f32_e32 v14, 0x3d372713, v0
	v_fma_f32 v14, v0, v14, 1.0
	v_mul_f32_e32 v9, 0x3d372713, v4
	v_mul_f32_e32 v10, 0x3d372713, v1
	v_fma_f32 v9, v4, v9, 1.0
	v_fma_f32 v10, v1, v10, 1.0
	v_mul_f32_e32 v9, v4, v9
	v_mul_f32_e32 v10, v1, v10
	v_mul_f32_e32 v9, 0x3fcc422a, v9
	v_mul_f32_e32 v10, 0x3fcc422a, v10
	v_mul_f32_e32 v9, 0xbfb8aa3b, v9
	v_mul_f32_e32 v10, 0xbfb8aa3b, v10
	v_exp_f32_e32 v9, v9
	v_exp_f32_e32 v10, v10
	v_mul_f32_e32 v14, v0, v14
	v_mul_f32_e32 v14, 0x3fcc422a, v14
	v_mul_f32_e32 v14, 0xbfb8aa3b, v14
	v_exp_f32_e32 v14, v14
	v_add_f32_e32 v9, 1.0, v9
	v_add_f32_e32 v10, 1.0, v10
	v_mul_f32_e32 v11, 0x3d372713, v5
	v_rcp_f32_e32 v9, v9
	v_rcp_f32_e32 v10, v10
	v_fma_f32 v11, v5, v11, 1.0
	v_mul_f32_e32 v11, v5, v11
	v_mul_f32_e32 v11, 0x3fcc422a, v11
	v_add_f32_e32 v8, 1.0, v14
	v_mul_f32_e32 v11, 0xbfb8aa3b, v11
	v_rcp_f32_e32 v8, v8
	v_exp_f32_e32 v11, v11
	v_mul_f32_e32 v4, v4, v9
	v_mul_f32_e32 v1, v1, v10
	v_mul_f32_e32 v9, 0x3d372713, v2
	v_mul_f32_e32 v10, 0x3d372713, v6
	v_fma_f32 v9, v2, v9, 1.0
	v_fma_f32 v10, v6, v10, 1.0
	v_mul_f32_e32 v9, v2, v9
	v_mul_f32_e32 v10, v6, v10
	v_mul_f32_e32 v9, 0x3fcc422a, v9
	v_mul_f32_e32 v10, 0x3fcc422a, v10
	v_mul_f32_e32 v0, v0, v8
	v_add_f32_e32 v8, 1.0, v11
	v_mul_f32_e32 v9, 0xbfb8aa3b, v9
	v_mul_f32_e32 v10, 0xbfb8aa3b, v10
	v_rcp_f32_e32 v8, v8
	v_exp_f32_e32 v9, v9
	v_exp_f32_e32 v10, v10
	v_mul_f32_e32 v11, 0x3d372713, v7
	v_mul_f32_e32 v5, v5, v8
	v_add_f32_e32 v8, 1.0, v9
	v_add_f32_e32 v9, 1.0, v10
	v_mul_f32_e32 v10, 0x3d372713, v3
	v_fma_f32 v10, v3, v10, 1.0
	v_mul_f32_e32 v10, v3, v10
	v_mul_f32_e32 v10, 0x3fcc422a, v10
	v_mul_f32_e32 v10, 0xbfb8aa3b, v10
	v_exp_f32_e32 v10, v10
	v_fma_f32 v11, v7, v11, 1.0
	v_mul_f32_e32 v11, v7, v11
	v_mul_f32_e32 v11, 0x3fcc422a, v11
	v_rcp_f32_e32 v8, v8
	v_mul_f32_e32 v11, 0xbfb8aa3b, v11
	v_add_f32_e32 v10, 1.0, v10
	v_exp_f32_e32 v11, v11
	v_rcp_f32_e32 v10, v10
	v_mul_f32_e32 v2, v2, v8
	v_cvt_pk_bf16_f32 v0, v0, v1
	v_add_f32_e32 v11, 1.0, v11
	v_mul_f32_e32 v3, v3, v10
	v_cvt_pk_bf16_f32 v1, v2, v3
	v_cvt_pk_bf16_f32 v2, v4, v5
	v_add_u32_e32 v4, v16, v112
	v_rcp_f32_e32 v9, v9
	v_rcp_f32_e32 v11, v11
	v_ashrrev_i32_e32 v5, 31, v4
	v_lshlrev_b64 v[4:5], 11, v[4:5]
	v_lshl_add_u64 v[4:5], s[14:15], 0, v[4:5]
	v_lshl_add_u64 v[4:5], v[4:5], 0, v[120:121]
	s_and_b64 vcc, exec, s[4:5]
	v_mul_f32_e32 v6, v6, v9
	v_mul_f32_e32 v7, v7, v11
	v_cvt_pk_bf16_f32 v3, v6, v7
	global_store_dwordx4 v[4:5], v[0:3], off sc1
	s_cbranch_vccnz .LBB0_1151
	s_andn2_b64 vcc, exec, s[12:13]
	s_cbranch_vccnz .LBB0_1141
	s_barrier
	s_branch .LBB0_1141
